# static priority: one s_setprio 1 for waves 4-7 per GEMM unit, all per-segment flips deleted
# speedup vs baseline: 1.0016x; 1.0016x over previous
.LBB0_271:
	s_ashr_i32 s63, s62, 31
	s_lshl_b64 s[0:1], s[62:63], 20
	s_add_u32 s66, s49, s0
	s_addc_u32 s67, s82, s1
	s_and_b64 s[0:1], s[4:5], exec
	s_cselect_b32 s0, s67, s75
	s_cselect_b32 s1, s66, s74
	s_ashr_i32 s65, s64, 31
	s_lshl_b64 s[68:69], s[64:65], 20
	s_add_u32 s68, s45, s68
	s_addc_u32 s69, s47, s69
	s_and_b64 s[78:79], s[4:5], exec
	s_cselect_b32 s3, s69, s77
	s_cselect_b32 s63, s68, s76
	s_add_u32 s74, s74, 0x80080
	s_addc_u32 s75, s75, 0
	s_add_u32 s65, s76, 0x100
	s_addc_u32 s71, s77, 0
	s_mov_b32 s90, -2
	s_waitcnt vmcnt(0)
	s_cmp_ge_u32 s97, 0x100
	s_cbranch_scc0 .Lkprio_0
	s_setprio 1
.Lkprio_0:
	ds_read_b128 v[146:149], v166
	ds_read_b128 v[150:153], v166 offset:1024
	ds_read_b128 v[154:157], v166 offset:2048
	ds_read_b128 v[170:173], v166 offset:3072
	ds_read_b128 v[174:177], v167
	ds_read_b128 v[178:181], v167 offset:1024
	ds_read_b128 v[182:185], v167 offset:2048
	ds_read_b128 v[186:189], v167 offset:3072
	s_add_u32 s76, s74, 0xfff80080
	s_addc_u32 s77, s75, -1
	s_cmp_eq_u32 s90, 28
	s_cselect_b32 s79, s0, s77
	s_cselect_b32 s78, s1, s76
	s_cselect_b32 s77, s3, s71
	s_cselect_b32 s76, s63, s65
	s_add_i32 m0, s31, 0xc000
	ds_read_b128 v[190:193], v168
	ds_read_b128 v[194:197], v168 offset:1024
	ds_read_b128 v[198:201], v168 offset:2048
	ds_read_b128 v[202:205], v168 offset:3072
	ds_read_b128 v[206:209], v168 offset:4096
	ds_read_b128 v[214:217], v168 offset:5120
	ds_read_b128 v[218:221], v168 offset:6144
	ds_read_b128 v[222:225], v168 offset:7168
	global_load_lds_dwordx4 v138, s[74:75]
	s_add_i32 m0, s31, 0xe000
	s_nop 0
	global_load_lds_dwordx4 v140, s[74:75]
	s_waitcnt vmcnt(8)
	s_waitcnt lgkmcnt(0)
	s_barrier
	v_mfma_f32_16x16x32_bf16 v[124:127], v[146:149], v[190:193], 0
	v_mfma_f32_16x16x32_bf16 v[120:123], v[154:157], v[190:193], 0
	v_mfma_f32_16x16x32_bf16 v[108:111], v[146:149], v[198:201], 0
	v_mfma_f32_16x16x32_bf16 v[104:107], v[154:157], v[198:201], 0
	v_mfma_f32_16x16x32_bf16 v[92:95], v[146:149], v[206:209], 0
	v_mfma_f32_16x16x32_bf16 v[88:91], v[154:157], v[206:209], 0
	v_mfma_f32_16x16x32_bf16 v[76:79], v[146:149], v[218:221], 0
	v_mfma_f32_16x16x32_bf16 v[72:75], v[154:157], v[218:221], 0
	v_mfma_f32_16x16x32_bf16 v[124:127], v[150:153], v[194:197], v[124:127]
	v_mfma_f32_16x16x32_bf16 v[120:123], v[170:173], v[194:197], v[120:123]
	v_mfma_f32_16x16x32_bf16 v[108:111], v[150:153], v[202:205], v[108:111]
	v_mfma_f32_16x16x32_bf16 v[104:107], v[170:173], v[202:205], v[104:107]
	v_mfma_f32_16x16x32_bf16 v[92:95], v[150:153], v[214:217], v[92:95]
	v_mfma_f32_16x16x32_bf16 v[88:91], v[170:173], v[214:217], v[88:91]
	v_mfma_f32_16x16x32_bf16 v[76:79], v[150:153], v[222:225], v[76:79]
	v_mfma_f32_16x16x32_bf16 v[72:75], v[170:173], v[222:225], v[72:75]
	v_mfma_f32_16x16x32_bf16 v[116:119], v[174:177], v[190:193], 0
	v_mfma_f32_16x16x32_bf16 v[112:115], v[182:185], v[190:193], 0
	v_mfma_f32_16x16x32_bf16 v[100:103], v[174:177], v[198:201], 0
	v_mfma_f32_16x16x32_bf16 v[96:99], v[182:185], v[198:201], 0
	v_mfma_f32_16x16x32_bf16 v[84:87], v[174:177], v[206:209], 0
	v_mfma_f32_16x16x32_bf16 v[80:83], v[182:185], v[206:209], 0
	v_mfma_f32_16x16x32_bf16 v[68:71], v[174:177], v[218:221], 0
	v_mfma_f32_16x16x32_bf16 v[64:67], v[182:185], v[218:221], 0
	v_mfma_f32_16x16x32_bf16 v[116:119], v[178:181], v[194:197], v[116:119]
	v_mfma_f32_16x16x32_bf16 v[112:115], v[186:189], v[194:197], v[112:115]
	v_mfma_f32_16x16x32_bf16 v[100:103], v[178:181], v[202:205], v[100:103]
	v_mfma_f32_16x16x32_bf16 v[96:99], v[186:189], v[202:205], v[96:99]
	v_mfma_f32_16x16x32_bf16 v[84:87], v[178:181], v[214:217], v[84:87]
	v_mfma_f32_16x16x32_bf16 v[80:83], v[186:189], v[214:217], v[80:83]
	v_mfma_f32_16x16x32_bf16 v[68:71], v[178:181], v[222:225], v[68:71]
	v_mfma_f32_16x16x32_bf16 v[64:67], v[186:189], v[222:225], v[64:67]
	s_barrier
	s_add_i32 s91, s81, s30
	s_add_u32 s98, s76, s34
	s_addc_u32 s99, s77, s35
	s_mov_b32 m0, s91
	ds_read_b128 v[190:193], v168 offset:16384
	ds_read_b128 v[194:197], v168 offset:17408
	ds_read_b128 v[198:201], v168 offset:18432
	ds_read_b128 v[202:205], v168 offset:19456
	ds_read_b128 v[206:209], v168 offset:20480
	ds_read_b128 v[214:217], v168 offset:21504
	ds_read_b128 v[218:221], v168 offset:22528
	ds_read_b128 v[222:225], v168 offset:23552
	global_load_lds_dwordx4 v130, s[76:77]
	s_add_i32 m0, s91, 0x2000
	s_add_u32 s92, s76, 0x80000
	s_addc_u32 s93, s77, 0
	s_add_i32 s91, s83, s30
	global_load_lds_dwordx4 v134, s[76:77]
	s_mov_b32 m0, s91
	s_add_u32 s100, s78, s34
	s_addc_u32 s101, s79, s35
	global_load_lds_dwordx4 v130, s[92:93]
	s_add_i32 m0, s91, 0x2000
	s_nop 0
	global_load_lds_dwordx4 v134, s[92:93]
	s_mov_b32 m0, s31
	s_nop 0
	global_load_lds_dwordx4 v128, s[78:79]
	s_mov_b32 m0, s51
	s_nop 0
	global_load_lds_dwordx4 v132, s[78:79]
	s_waitcnt vmcnt(8)
	s_waitcnt lgkmcnt(0)
	s_barrier
	v_mfma_f32_16x16x32_bf16 v[60:63], v[146:149], v[190:193], 0
	v_mfma_f32_16x16x32_bf16 v[56:59], v[154:157], v[190:193], 0
	v_mfma_f32_16x16x32_bf16 v[44:47], v[146:149], v[198:201], 0
	v_mfma_f32_16x16x32_bf16 v[40:43], v[154:157], v[198:201], 0
	v_mfma_f32_16x16x32_bf16 v[28:31], v[146:149], v[206:209], 0
	v_mfma_f32_16x16x32_bf16 v[24:27], v[154:157], v[206:209], 0
	v_mfma_f32_16x16x32_bf16 v[12:15], v[146:149], v[218:221], 0
	v_mfma_f32_16x16x32_bf16 v[8:11], v[154:157], v[218:221], 0
	v_mfma_f32_16x16x32_bf16 v[60:63], v[150:153], v[194:197], v[60:63]
	v_mfma_f32_16x16x32_bf16 v[56:59], v[170:173], v[194:197], v[56:59]
	v_mfma_f32_16x16x32_bf16 v[44:47], v[150:153], v[202:205], v[44:47]
	v_mfma_f32_16x16x32_bf16 v[40:43], v[170:173], v[202:205], v[40:43]
	v_mfma_f32_16x16x32_bf16 v[28:31], v[150:153], v[214:217], v[28:31]
	v_mfma_f32_16x16x32_bf16 v[24:27], v[170:173], v[214:217], v[24:27]
	v_mfma_f32_16x16x32_bf16 v[12:15], v[150:153], v[222:225], v[12:15]
	v_mfma_f32_16x16x32_bf16 v[8:11], v[170:173], v[222:225], v[8:11]
	v_mfma_f32_16x16x32_bf16 v[52:55], v[174:177], v[190:193], 0
	v_mfma_f32_16x16x32_bf16 v[48:51], v[182:185], v[190:193], 0
	v_mfma_f32_16x16x32_bf16 v[36:39], v[174:177], v[198:201], 0
	v_mfma_f32_16x16x32_bf16 v[32:35], v[182:185], v[198:201], 0
	v_mfma_f32_16x16x32_bf16 v[20:23], v[174:177], v[206:209], 0
	v_mfma_f32_16x16x32_bf16 v[16:19], v[182:185], v[206:209], 0
	v_mfma_f32_16x16x32_bf16 v[4:7], v[174:177], v[218:221], 0
	v_mfma_f32_16x16x32_bf16 v[0:3], v[182:185], v[218:221], 0
	v_mfma_f32_16x16x32_bf16 v[52:55], v[178:181], v[194:197], v[52:55]
	v_mfma_f32_16x16x32_bf16 v[48:51], v[186:189], v[194:197], v[48:51]
	v_mfma_f32_16x16x32_bf16 v[36:39], v[178:181], v[202:205], v[36:39]
	v_mfma_f32_16x16x32_bf16 v[32:35], v[186:189], v[202:205], v[32:35]
	v_mfma_f32_16x16x32_bf16 v[20:23], v[178:181], v[214:217], v[20:23]
	v_mfma_f32_16x16x32_bf16 v[16:19], v[186:189], v[214:217], v[16:19]
	v_mfma_f32_16x16x32_bf16 v[4:7], v[178:181], v[222:225], v[4:7]
	v_mfma_f32_16x16x32_bf16 v[0:3], v[186:189], v[222:225], v[0:3]
	s_barrier
	s_add_i32 s91, 0, 0x18000
	v_add_u32_e32 v136, s91, v162
	s_add_i32 s92, 0, 0x1c000
	ds_read_b128 v[146:149], v136
	ds_read_b128 v[150:153], v136 offset:1024
	ds_read_b128 v[154:157], v136 offset:2048
	ds_read_b128 v[170:173], v136 offset:3072
	v_add_u32_e32 v136, s92, v162
	ds_read_b128 v[174:177], v136
	ds_read_b128 v[178:181], v136 offset:1024
	ds_read_b128 v[182:185], v136 offset:2048
	ds_read_b128 v[186:189], v136 offset:3072
	s_add_u32 s78, s78, 0x80000
	s_addc_u32 s79, s79, 0
	s_mov_b32 m0, s28
	ds_read_b128 v[190:193], v168 offset:32768
	ds_read_b128 v[194:197], v168 offset:33792
	ds_read_b128 v[198:201], v168 offset:34816
	ds_read_b128 v[202:205], v168 offset:35840
	ds_read_b128 v[206:209], v168 offset:36864
	ds_read_b128 v[214:217], v168 offset:37888
	ds_read_b128 v[218:221], v168 offset:38912
	ds_read_b128 v[222:225], v168 offset:39936
	global_load_lds_dwordx4 v128, s[78:79]
	s_mov_b32 m0, s29
	s_nop 0
	global_load_lds_dwordx4 v132, s[78:79]
	s_waitcnt vmcnt(8)
	s_waitcnt lgkmcnt(0)
	s_barrier
	v_mfma_f32_16x16x32_bf16 v[124:127], v[146:149], v[190:193], v[124:127]
	v_mfma_f32_16x16x32_bf16 v[120:123], v[154:157], v[190:193], v[120:123]
	v_mfma_f32_16x16x32_bf16 v[108:111], v[146:149], v[198:201], v[108:111]
	v_mfma_f32_16x16x32_bf16 v[104:107], v[154:157], v[198:201], v[104:107]
	v_mfma_f32_16x16x32_bf16 v[92:95], v[146:149], v[206:209], v[92:95]
	v_mfma_f32_16x16x32_bf16 v[88:91], v[154:157], v[206:209], v[88:91]
	v_mfma_f32_16x16x32_bf16 v[76:79], v[146:149], v[218:221], v[76:79]
	v_mfma_f32_16x16x32_bf16 v[72:75], v[154:157], v[218:221], v[72:75]
	v_mfma_f32_16x16x32_bf16 v[124:127], v[150:153], v[194:197], v[124:127]
	v_mfma_f32_16x16x32_bf16 v[120:123], v[170:173], v[194:197], v[120:123]
	v_mfma_f32_16x16x32_bf16 v[108:111], v[150:153], v[202:205], v[108:111]
	v_mfma_f32_16x16x32_bf16 v[104:107], v[170:173], v[202:205], v[104:107]
	v_mfma_f32_16x16x32_bf16 v[92:95], v[150:153], v[214:217], v[92:95]
	v_mfma_f32_16x16x32_bf16 v[88:91], v[170:173], v[214:217], v[88:91]
	v_mfma_f32_16x16x32_bf16 v[76:79], v[150:153], v[222:225], v[76:79]
	v_mfma_f32_16x16x32_bf16 v[72:75], v[170:173], v[222:225], v[72:75]
	v_mfma_f32_16x16x32_bf16 v[116:119], v[174:177], v[190:193], v[116:119]
	v_mfma_f32_16x16x32_bf16 v[112:115], v[182:185], v[190:193], v[112:115]
	v_mfma_f32_16x16x32_bf16 v[100:103], v[174:177], v[198:201], v[100:103]
	v_mfma_f32_16x16x32_bf16 v[96:99], v[182:185], v[198:201], v[96:99]
	v_mfma_f32_16x16x32_bf16 v[84:87], v[174:177], v[206:209], v[84:87]
	v_mfma_f32_16x16x32_bf16 v[80:83], v[182:185], v[206:209], v[80:83]
	v_mfma_f32_16x16x32_bf16 v[68:71], v[174:177], v[218:221], v[68:71]
	v_mfma_f32_16x16x32_bf16 v[64:67], v[182:185], v[218:221], v[64:67]
	v_mfma_f32_16x16x32_bf16 v[116:119], v[178:181], v[194:197], v[116:119]
	v_mfma_f32_16x16x32_bf16 v[112:115], v[186:189], v[194:197], v[112:115]
	v_mfma_f32_16x16x32_bf16 v[100:103], v[178:181], v[202:205], v[100:103]
	v_mfma_f32_16x16x32_bf16 v[96:99], v[186:189], v[202:205], v[96:99]
	v_mfma_f32_16x16x32_bf16 v[84:87], v[178:181], v[214:217], v[84:87]
	v_mfma_f32_16x16x32_bf16 v[80:83], v[186:189], v[214:217], v[80:83]
	v_mfma_f32_16x16x32_bf16 v[68:71], v[178:181], v[222:225], v[68:71]
	v_mfma_f32_16x16x32_bf16 v[64:67], v[186:189], v[222:225], v[64:67]
	s_barrier
	s_add_i32 s78, s91, s30
	s_mov_b32 m0, s78
	ds_read_b128 v[190:193], v168 offset:49152
	ds_read_b128 v[194:197], v168 offset:50176
	ds_read_b128 v[198:201], v168 offset:51200
	ds_read_b128 v[202:205], v168 offset:52224
	ds_read_b128 v[206:209], v168 offset:53248
	ds_read_b128 v[214:217], v168 offset:54272
	ds_read_b128 v[218:221], v168 offset:55296
	ds_read_b128 v[222:225], v168 offset:56320
	global_load_lds_dwordx4 v130, s[98:99]
	s_add_i32 m0, s78, 0x2000
	s_add_u32 s76, s76, 0x80080
	s_addc_u32 s77, s77, 0
	s_add_i32 s78, s92, s30
	global_load_lds_dwordx4 v134, s[98:99]
	s_mov_b32 m0, s78
	s_nop 0
	global_load_lds_dwordx4 v130, s[76:77]
	s_add_i32 m0, s78, 0x2000
	s_nop 0
	global_load_lds_dwordx4 v134, s[76:77]
	s_mov_b32 m0, s73
	s_nop 0
	global_load_lds_dwordx4 v128, s[100:101]
	s_mov_b32 m0, s80
	s_nop 0
	global_load_lds_dwordx4 v132, s[100:101]
	s_waitcnt vmcnt(8)
	s_waitcnt lgkmcnt(0)
	s_barrier
	v_mfma_f32_16x16x32_bf16 v[60:63], v[146:149], v[190:193], v[60:63]
	v_mfma_f32_16x16x32_bf16 v[56:59], v[154:157], v[190:193], v[56:59]
	v_mfma_f32_16x16x32_bf16 v[44:47], v[146:149], v[198:201], v[44:47]
	v_mfma_f32_16x16x32_bf16 v[40:43], v[154:157], v[198:201], v[40:43]
	v_mfma_f32_16x16x32_bf16 v[28:31], v[146:149], v[206:209], v[28:31]
	v_mfma_f32_16x16x32_bf16 v[24:27], v[154:157], v[206:209], v[24:27]
	v_mfma_f32_16x16x32_bf16 v[12:15], v[146:149], v[218:221], v[12:15]
	v_mfma_f32_16x16x32_bf16 v[8:11], v[154:157], v[218:221], v[8:11]
	v_mfma_f32_16x16x32_bf16 v[60:63], v[150:153], v[194:197], v[60:63]
	v_mfma_f32_16x16x32_bf16 v[56:59], v[170:173], v[194:197], v[56:59]
	v_mfma_f32_16x16x32_bf16 v[44:47], v[150:153], v[202:205], v[44:47]
	v_mfma_f32_16x16x32_bf16 v[40:43], v[170:173], v[202:205], v[40:43]
	v_mfma_f32_16x16x32_bf16 v[28:31], v[150:153], v[214:217], v[28:31]
	v_mfma_f32_16x16x32_bf16 v[24:27], v[170:173], v[214:217], v[24:27]
	v_mfma_f32_16x16x32_bf16 v[12:15], v[150:153], v[222:225], v[12:15]
	v_mfma_f32_16x16x32_bf16 v[8:11], v[170:173], v[222:225], v[8:11]
	v_mfma_f32_16x16x32_bf16 v[52:55], v[174:177], v[190:193], v[52:55]
	v_mfma_f32_16x16x32_bf16 v[48:51], v[182:185], v[190:193], v[48:51]
	v_mfma_f32_16x16x32_bf16 v[36:39], v[174:177], v[198:201], v[36:39]
	v_mfma_f32_16x16x32_bf16 v[32:35], v[182:185], v[198:201], v[32:35]
	v_mfma_f32_16x16x32_bf16 v[20:23], v[174:177], v[206:209], v[20:23]
	v_mfma_f32_16x16x32_bf16 v[16:19], v[182:185], v[206:209], v[16:19]
	v_mfma_f32_16x16x32_bf16 v[4:7], v[174:177], v[218:221], v[4:7]
	v_mfma_f32_16x16x32_bf16 v[0:3], v[182:185], v[218:221], v[0:3]
	v_mfma_f32_16x16x32_bf16 v[52:55], v[178:181], v[194:197], v[52:55]
	v_mfma_f32_16x16x32_bf16 v[48:51], v[186:189], v[194:197], v[48:51]
	v_mfma_f32_16x16x32_bf16 v[36:39], v[178:181], v[202:205], v[36:39]
	v_mfma_f32_16x16x32_bf16 v[32:35], v[186:189], v[202:205], v[32:35]
	v_mfma_f32_16x16x32_bf16 v[20:23], v[178:181], v[214:217], v[20:23]
	v_mfma_f32_16x16x32_bf16 v[16:19], v[186:189], v[214:217], v[16:19]
	v_mfma_f32_16x16x32_bf16 v[4:7], v[178:181], v[222:225], v[4:7]
	v_mfma_f32_16x16x32_bf16 v[0:3], v[186:189], v[222:225], v[0:3]
	s_barrier
	s_add_i32 s90, s90, 2
	s_add_u32 s74, s74, 0x100
	s_addc_u32 s75, s75, 0
	s_add_u32 s65, s65, 0x100
	s_addc_u32 s71, s71, 0
	s_cmp_gt_u32 s90, 29
.LBB0_272:
	ds_read_b128 v[146:149], v166
	ds_read_b128 v[150:153], v166 offset:1024
	ds_read_b128 v[154:157], v166 offset:2048
	ds_read_b128 v[170:173], v166 offset:3072
	ds_read_b128 v[174:177], v167
	ds_read_b128 v[178:181], v167 offset:1024
	ds_read_b128 v[182:185], v167 offset:2048
	ds_read_b128 v[186:189], v167 offset:3072
	s_add_u32 s76, s74, 0xfff80080
	s_addc_u32 s77, s75, -1
	s_cmp_eq_u32 s90, 28
	s_cselect_b32 s79, s0, s77
	s_cselect_b32 s78, s1, s76
	s_cselect_b32 s77, s3, s71
	s_cselect_b32 s76, s63, s65
	s_add_i32 m0, s31, 0xc000
	ds_read_b128 v[190:193], v168
	ds_read_b128 v[194:197], v168 offset:1024
	ds_read_b128 v[198:201], v168 offset:2048
	ds_read_b128 v[202:205], v168 offset:3072
	ds_read_b128 v[206:209], v168 offset:4096
	ds_read_b128 v[214:217], v168 offset:5120
	ds_read_b128 v[218:221], v168 offset:6144
	ds_read_b128 v[222:225], v168 offset:7168
	global_load_lds_dwordx4 v138, s[74:75]
	s_add_i32 m0, s31, 0xe000
	s_nop 0
	global_load_lds_dwordx4 v140, s[74:75]
	s_waitcnt vmcnt(8)
	s_waitcnt lgkmcnt(0)
	s_barrier
	v_mfma_f32_16x16x32_bf16 v[124:127], v[146:149], v[190:193], v[124:127]
	v_mfma_f32_16x16x32_bf16 v[120:123], v[154:157], v[190:193], v[120:123]
	v_mfma_f32_16x16x32_bf16 v[108:111], v[146:149], v[198:201], v[108:111]
	v_mfma_f32_16x16x32_bf16 v[104:107], v[154:157], v[198:201], v[104:107]
	v_mfma_f32_16x16x32_bf16 v[92:95], v[146:149], v[206:209], v[92:95]
	v_mfma_f32_16x16x32_bf16 v[88:91], v[154:157], v[206:209], v[88:91]
	v_mfma_f32_16x16x32_bf16 v[76:79], v[146:149], v[218:221], v[76:79]
	v_mfma_f32_16x16x32_bf16 v[72:75], v[154:157], v[218:221], v[72:75]
	v_mfma_f32_16x16x32_bf16 v[124:127], v[150:153], v[194:197], v[124:127]
	v_mfma_f32_16x16x32_bf16 v[120:123], v[170:173], v[194:197], v[120:123]
	v_mfma_f32_16x16x32_bf16 v[108:111], v[150:153], v[202:205], v[108:111]
	v_mfma_f32_16x16x32_bf16 v[104:107], v[170:173], v[202:205], v[104:107]
	v_mfma_f32_16x16x32_bf16 v[92:95], v[150:153], v[214:217], v[92:95]
	v_mfma_f32_16x16x32_bf16 v[88:91], v[170:173], v[214:217], v[88:91]
	v_mfma_f32_16x16x32_bf16 v[76:79], v[150:153], v[222:225], v[76:79]
	v_mfma_f32_16x16x32_bf16 v[72:75], v[170:173], v[222:225], v[72:75]
	v_mfma_f32_16x16x32_bf16 v[116:119], v[174:177], v[190:193], v[116:119]
	v_mfma_f32_16x16x32_bf16 v[112:115], v[182:185], v[190:193], v[112:115]
	v_mfma_f32_16x16x32_bf16 v[100:103], v[174:177], v[198:201], v[100:103]
	v_mfma_f32_16x16x32_bf16 v[96:99], v[182:185], v[198:201], v[96:99]
	v_mfma_f32_16x16x32_bf16 v[84:87], v[174:177], v[206:209], v[84:87]
	v_mfma_f32_16x16x32_bf16 v[80:83], v[182:185], v[206:209], v[80:83]
	v_mfma_f32_16x16x32_bf16 v[68:71], v[174:177], v[218:221], v[68:71]
	v_mfma_f32_16x16x32_bf16 v[64:67], v[182:185], v[218:221], v[64:67]
	v_mfma_f32_16x16x32_bf16 v[116:119], v[178:181], v[194:197], v[116:119]
	v_mfma_f32_16x16x32_bf16 v[112:115], v[186:189], v[194:197], v[112:115]
	v_mfma_f32_16x16x32_bf16 v[100:103], v[178:181], v[202:205], v[100:103]
	v_mfma_f32_16x16x32_bf16 v[96:99], v[186:189], v[202:205], v[96:99]
	v_mfma_f32_16x16x32_bf16 v[84:87], v[178:181], v[214:217], v[84:87]
	v_mfma_f32_16x16x32_bf16 v[80:83], v[186:189], v[214:217], v[80:83]
	v_mfma_f32_16x16x32_bf16 v[68:71], v[178:181], v[222:225], v[68:71]
	v_mfma_f32_16x16x32_bf16 v[64:67], v[186:189], v[222:225], v[64:67]
	s_barrier
	s_add_i32 s91, s81, s30
	s_add_u32 s98, s76, s34
	s_addc_u32 s99, s77, s35
	s_mov_b32 m0, s91
	ds_read_b128 v[190:193], v168 offset:16384
	ds_read_b128 v[194:197], v168 offset:17408
	ds_read_b128 v[198:201], v168 offset:18432
	ds_read_b128 v[202:205], v168 offset:19456
	ds_read_b128 v[206:209], v168 offset:20480
	ds_read_b128 v[214:217], v168 offset:21504
	ds_read_b128 v[218:221], v168 offset:22528
	ds_read_b128 v[222:225], v168 offset:23552
	global_load_lds_dwordx4 v130, s[76:77]
	s_add_i32 m0, s91, 0x2000
	s_add_u32 s92, s76, 0x80000
	s_addc_u32 s93, s77, 0
	s_add_i32 s91, s83, s30
	global_load_lds_dwordx4 v134, s[76:77]
	s_mov_b32 m0, s91
	s_add_u32 s100, s78, s34
	s_addc_u32 s101, s79, s35
	global_load_lds_dwordx4 v130, s[92:93]
	s_add_i32 m0, s91, 0x2000
	s_nop 0
	global_load_lds_dwordx4 v134, s[92:93]
	s_mov_b32 m0, s31
	s_nop 0
	global_load_lds_dwordx4 v128, s[78:79]
	s_mov_b32 m0, s51
	s_nop 0
	global_load_lds_dwordx4 v132, s[78:79]
	s_waitcnt vmcnt(8)
	s_waitcnt lgkmcnt(0)
	s_barrier
	v_mfma_f32_16x16x32_bf16 v[60:63], v[146:149], v[190:193], v[60:63]
	v_mfma_f32_16x16x32_bf16 v[56:59], v[154:157], v[190:193], v[56:59]
	v_mfma_f32_16x16x32_bf16 v[44:47], v[146:149], v[198:201], v[44:47]
	v_mfma_f32_16x16x32_bf16 v[40:43], v[154:157], v[198:201], v[40:43]
	v_mfma_f32_16x16x32_bf16 v[28:31], v[146:149], v[206:209], v[28:31]
	v_mfma_f32_16x16x32_bf16 v[24:27], v[154:157], v[206:209], v[24:27]
	v_mfma_f32_16x16x32_bf16 v[12:15], v[146:149], v[218:221], v[12:15]
	v_mfma_f32_16x16x32_bf16 v[8:11], v[154:157], v[218:221], v[8:11]
	v_mfma_f32_16x16x32_bf16 v[60:63], v[150:153], v[194:197], v[60:63]
	v_mfma_f32_16x16x32_bf16 v[56:59], v[170:173], v[194:197], v[56:59]
	v_mfma_f32_16x16x32_bf16 v[44:47], v[150:153], v[202:205], v[44:47]
	v_mfma_f32_16x16x32_bf16 v[40:43], v[170:173], v[202:205], v[40:43]
	v_mfma_f32_16x16x32_bf16 v[28:31], v[150:153], v[214:217], v[28:31]
	v_mfma_f32_16x16x32_bf16 v[24:27], v[170:173], v[214:217], v[24:27]
	v_mfma_f32_16x16x32_bf16 v[12:15], v[150:153], v[222:225], v[12:15]
	v_mfma_f32_16x16x32_bf16 v[8:11], v[170:173], v[222:225], v[8:11]
	v_mfma_f32_16x16x32_bf16 v[52:55], v[174:177], v[190:193], v[52:55]
	v_mfma_f32_16x16x32_bf16 v[48:51], v[182:185], v[190:193], v[48:51]
	v_mfma_f32_16x16x32_bf16 v[36:39], v[174:177], v[198:201], v[36:39]
	v_mfma_f32_16x16x32_bf16 v[32:35], v[182:185], v[198:201], v[32:35]
	v_mfma_f32_16x16x32_bf16 v[20:23], v[174:177], v[206:209], v[20:23]
	v_mfma_f32_16x16x32_bf16 v[16:19], v[182:185], v[206:209], v[16:19]
	v_mfma_f32_16x16x32_bf16 v[4:7], v[174:177], v[218:221], v[4:7]
	v_mfma_f32_16x16x32_bf16 v[0:3], v[182:185], v[218:221], v[0:3]
	v_mfma_f32_16x16x32_bf16 v[52:55], v[178:181], v[194:197], v[52:55]
	v_mfma_f32_16x16x32_bf16 v[48:51], v[186:189], v[194:197], v[48:51]
	v_mfma_f32_16x16x32_bf16 v[36:39], v[178:181], v[202:205], v[36:39]
	v_mfma_f32_16x16x32_bf16 v[32:35], v[186:189], v[202:205], v[32:35]
	v_mfma_f32_16x16x32_bf16 v[20:23], v[178:181], v[214:217], v[20:23]
	v_mfma_f32_16x16x32_bf16 v[16:19], v[186:189], v[214:217], v[16:19]
	v_mfma_f32_16x16x32_bf16 v[4:7], v[178:181], v[222:225], v[4:7]
	v_mfma_f32_16x16x32_bf16 v[0:3], v[186:189], v[222:225], v[0:3]
	s_barrier
	s_add_i32 s91, 0, 0x18000
	v_add_u32_e32 v136, s91, v162
	s_add_i32 s92, 0, 0x1c000
	ds_read_b128 v[146:149], v136
	ds_read_b128 v[150:153], v136 offset:1024
	ds_read_b128 v[154:157], v136 offset:2048
	ds_read_b128 v[170:173], v136 offset:3072
	v_add_u32_e32 v136, s92, v162
	ds_read_b128 v[174:177], v136
	ds_read_b128 v[178:181], v136 offset:1024
	ds_read_b128 v[182:185], v136 offset:2048
	ds_read_b128 v[186:189], v136 offset:3072
	s_add_u32 s78, s78, 0x80000
	s_addc_u32 s79, s79, 0
	s_mov_b32 m0, s28
	ds_read_b128 v[190:193], v168 offset:32768
	ds_read_b128 v[194:197], v168 offset:33792
	ds_read_b128 v[198:201], v168 offset:34816
	ds_read_b128 v[202:205], v168 offset:35840
	ds_read_b128 v[206:209], v168 offset:36864
	ds_read_b128 v[214:217], v168 offset:37888
	ds_read_b128 v[218:221], v168 offset:38912
	ds_read_b128 v[222:225], v168 offset:39936
	global_load_lds_dwordx4 v128, s[78:79]
	s_mov_b32 m0, s29
	s_nop 0
	global_load_lds_dwordx4 v132, s[78:79]
	s_waitcnt vmcnt(8)
	s_waitcnt lgkmcnt(0)
	s_barrier
	v_mfma_f32_16x16x32_bf16 v[124:127], v[146:149], v[190:193], v[124:127]
	v_mfma_f32_16x16x32_bf16 v[120:123], v[154:157], v[190:193], v[120:123]
	v_mfma_f32_16x16x32_bf16 v[108:111], v[146:149], v[198:201], v[108:111]
	v_mfma_f32_16x16x32_bf16 v[104:107], v[154:157], v[198:201], v[104:107]
	v_mfma_f32_16x16x32_bf16 v[92:95], v[146:149], v[206:209], v[92:95]
	v_mfma_f32_16x16x32_bf16 v[88:91], v[154:157], v[206:209], v[88:91]
	v_mfma_f32_16x16x32_bf16 v[76:79], v[146:149], v[218:221], v[76:79]
	v_mfma_f32_16x16x32_bf16 v[72:75], v[154:157], v[218:221], v[72:75]
	v_mfma_f32_16x16x32_bf16 v[124:127], v[150:153], v[194:197], v[124:127]
	v_mfma_f32_16x16x32_bf16 v[120:123], v[170:173], v[194:197], v[120:123]
	v_mfma_f32_16x16x32_bf16 v[108:111], v[150:153], v[202:205], v[108:111]
	v_mfma_f32_16x16x32_bf16 v[104:107], v[170:173], v[202:205], v[104:107]
	v_mfma_f32_16x16x32_bf16 v[92:95], v[150:153], v[214:217], v[92:95]
	v_mfma_f32_16x16x32_bf16 v[88:91], v[170:173], v[214:217], v[88:91]
	v_mfma_f32_16x16x32_bf16 v[76:79], v[150:153], v[222:225], v[76:79]
	v_mfma_f32_16x16x32_bf16 v[72:75], v[170:173], v[222:225], v[72:75]
	v_mfma_f32_16x16x32_bf16 v[116:119], v[174:177], v[190:193], v[116:119]
	v_mfma_f32_16x16x32_bf16 v[112:115], v[182:185], v[190:193], v[112:115]
	v_mfma_f32_16x16x32_bf16 v[100:103], v[174:177], v[198:201], v[100:103]
	v_mfma_f32_16x16x32_bf16 v[96:99], v[182:185], v[198:201], v[96:99]
	v_mfma_f32_16x16x32_bf16 v[84:87], v[174:177], v[206:209], v[84:87]
	v_mfma_f32_16x16x32_bf16 v[80:83], v[182:185], v[206:209], v[80:83]
	v_mfma_f32_16x16x32_bf16 v[68:71], v[174:177], v[218:221], v[68:71]
	v_mfma_f32_16x16x32_bf16 v[64:67], v[182:185], v[218:221], v[64:67]
	v_mfma_f32_16x16x32_bf16 v[116:119], v[178:181], v[194:197], v[116:119]
	v_mfma_f32_16x16x32_bf16 v[112:115], v[186:189], v[194:197], v[112:115]
	v_mfma_f32_16x16x32_bf16 v[100:103], v[178:181], v[202:205], v[100:103]
	v_mfma_f32_16x16x32_bf16 v[96:99], v[186:189], v[202:205], v[96:99]
	v_mfma_f32_16x16x32_bf16 v[84:87], v[178:181], v[214:217], v[84:87]
	v_mfma_f32_16x16x32_bf16 v[80:83], v[186:189], v[214:217], v[80:83]
	v_mfma_f32_16x16x32_bf16 v[68:71], v[178:181], v[222:225], v[68:71]
	v_mfma_f32_16x16x32_bf16 v[64:67], v[186:189], v[222:225], v[64:67]
	s_barrier
	s_add_i32 s78, s91, s30
	s_mov_b32 m0, s78
	ds_read_b128 v[190:193], v168 offset:49152
	ds_read_b128 v[194:197], v168 offset:50176
	ds_read_b128 v[198:201], v168 offset:51200
	ds_read_b128 v[202:205], v168 offset:52224
	ds_read_b128 v[206:209], v168 offset:53248
	ds_read_b128 v[214:217], v168 offset:54272
	ds_read_b128 v[218:221], v168 offset:55296
	ds_read_b128 v[222:225], v168 offset:56320
	global_load_lds_dwordx4 v130, s[98:99]
	s_add_i32 m0, s78, 0x2000
	s_add_u32 s76, s76, 0x80080
	s_addc_u32 s77, s77, 0
	s_add_i32 s78, s92, s30
	global_load_lds_dwordx4 v134, s[98:99]
	s_mov_b32 m0, s78
	s_nop 0
	global_load_lds_dwordx4 v130, s[76:77]
	s_add_i32 m0, s78, 0x2000
	s_nop 0
	global_load_lds_dwordx4 v134, s[76:77]
	s_mov_b32 m0, s73
	s_nop 0
	global_load_lds_dwordx4 v128, s[100:101]
	s_mov_b32 m0, s80
	s_nop 0
	global_load_lds_dwordx4 v132, s[100:101]
	s_waitcnt vmcnt(8)
	s_waitcnt lgkmcnt(0)
	s_barrier
	v_mfma_f32_16x16x32_bf16 v[60:63], v[146:149], v[190:193], v[60:63]
	v_mfma_f32_16x16x32_bf16 v[56:59], v[154:157], v[190:193], v[56:59]
	v_mfma_f32_16x16x32_bf16 v[44:47], v[146:149], v[198:201], v[44:47]
	v_mfma_f32_16x16x32_bf16 v[40:43], v[154:157], v[198:201], v[40:43]
	v_mfma_f32_16x16x32_bf16 v[28:31], v[146:149], v[206:209], v[28:31]
	v_mfma_f32_16x16x32_bf16 v[24:27], v[154:157], v[206:209], v[24:27]
	v_mfma_f32_16x16x32_bf16 v[12:15], v[146:149], v[218:221], v[12:15]
	v_mfma_f32_16x16x32_bf16 v[8:11], v[154:157], v[218:221], v[8:11]
	v_mfma_f32_16x16x32_bf16 v[60:63], v[150:153], v[194:197], v[60:63]
	v_mfma_f32_16x16x32_bf16 v[56:59], v[170:173], v[194:197], v[56:59]
	v_mfma_f32_16x16x32_bf16 v[44:47], v[150:153], v[202:205], v[44:47]
	v_mfma_f32_16x16x32_bf16 v[40:43], v[170:173], v[202:205], v[40:43]
	v_mfma_f32_16x16x32_bf16 v[28:31], v[150:153], v[214:217], v[28:31]
	v_mfma_f32_16x16x32_bf16 v[24:27], v[170:173], v[214:217], v[24:27]
	v_mfma_f32_16x16x32_bf16 v[12:15], v[150:153], v[222:225], v[12:15]
	v_mfma_f32_16x16x32_bf16 v[8:11], v[170:173], v[222:225], v[8:11]
	v_mfma_f32_16x16x32_bf16 v[52:55], v[174:177], v[190:193], v[52:55]
	v_mfma_f32_16x16x32_bf16 v[48:51], v[182:185], v[190:193], v[48:51]
	v_mfma_f32_16x16x32_bf16 v[36:39], v[174:177], v[198:201], v[36:39]
	v_mfma_f32_16x16x32_bf16 v[32:35], v[182:185], v[198:201], v[32:35]
	v_mfma_f32_16x16x32_bf16 v[20:23], v[174:177], v[206:209], v[20:23]
	v_mfma_f32_16x16x32_bf16 v[16:19], v[182:185], v[206:209], v[16:19]
	v_mfma_f32_16x16x32_bf16 v[4:7], v[174:177], v[218:221], v[4:7]
	v_mfma_f32_16x16x32_bf16 v[0:3], v[182:185], v[218:221], v[0:3]
	v_mfma_f32_16x16x32_bf16 v[52:55], v[178:181], v[194:197], v[52:55]
	v_mfma_f32_16x16x32_bf16 v[48:51], v[186:189], v[194:197], v[48:51]
	v_mfma_f32_16x16x32_bf16 v[36:39], v[178:181], v[202:205], v[36:39]
	v_mfma_f32_16x16x32_bf16 v[32:35], v[186:189], v[202:205], v[32:35]
	v_mfma_f32_16x16x32_bf16 v[20:23], v[178:181], v[214:217], v[20:23]
	v_mfma_f32_16x16x32_bf16 v[16:19], v[186:189], v[214:217], v[16:19]
	v_mfma_f32_16x16x32_bf16 v[4:7], v[178:181], v[222:225], v[4:7]
	v_mfma_f32_16x16x32_bf16 v[0:3], v[186:189], v[222:225], v[0:3]
	s_barrier
	s_add_i32 s90, s90, 2
	s_add_u32 s74, s74, 0x100
	s_addc_u32 s75, s75, 0
	s_add_u32 s65, s65, 0x100
	s_addc_u32 s71, s71, 0
	s_cmp_gt_u32 s90, 29
	s_cbranch_scc0 .LBB0_272
	s_setprio 0
	s_and_b64 vcc, exec, s[36:37]
	s_cbranch_vccz .LBB0_275
	s_barrier

.LBB0_542:
	s_ashr_i32 s35, s34, 31
	s_lshl_b64 s[0:1], s[34:35], 20
	s_add_u32 s36, s29, s0
	s_addc_u32 s37, s30, s1
	s_and_b64 s[0:1], s[6:7], exec
	s_cselect_b32 s0, s37, s43
	s_cselect_b32 s1, s36, s42
	s_ashr_i32 s25, s24, 31
	s_lshl_b64 s[38:39], s[24:25], 20
	s_add_u32 s38, s27, s38
	s_addc_u32 s39, s28, s39
	s_and_b64 s[46:47], s[6:7], exec
	s_cselect_b32 s3, s39, s45
	s_cselect_b32 s9, s38, s44
	s_add_u32 s42, s42, 0x80080
	s_addc_u32 s43, s43, 0
	s_add_u32 s25, s44, 0x100
	s_addc_u32 s35, s45, 0
	s_mov_b32 s58, -2
	s_waitcnt lgkmcnt(0)
	s_waitcnt vmcnt(0)
	s_cmp_ge_u32 s97, 0x100
	s_cbranch_scc0 .Lkprio_1
	s_setprio 1
.Lkprio_1:
	ds_read_b128 v[128:131], v216
	ds_read_b128 v[132:135], v216 offset:1024
	ds_read_b128 v[136:139], v216 offset:2048
	ds_read_b128 v[140:143], v216 offset:3072
	ds_read_b128 v[144:147], v217
	ds_read_b128 v[148:151], v217 offset:1024
	ds_read_b128 v[152:155], v217 offset:2048
	ds_read_b128 v[156:159], v217 offset:3072
	s_add_u32 s44, s42, 0xfff80080
	s_addc_u32 s45, s43, -1
	s_cmp_eq_u32 s58, 28
	s_cselect_b32 s47, s0, s45
	s_cselect_b32 s46, s1, s44
	s_cselect_b32 s45, s3, s35
	s_cselect_b32 s44, s9, s25
	s_add_i32 m0, s41, 0xc000
	ds_read_b128 v[160:163], v218
	ds_read_b128 v[164:167], v218 offset:1024
	ds_read_b128 v[168:171], v218 offset:2048
	ds_read_b128 v[172:175], v218 offset:3072
	ds_read_b128 v[192:195], v218 offset:4096
	ds_read_b128 v[196:199], v218 offset:5120
	ds_read_b128 v[200:203], v218 offset:6144
	ds_read_b128 v[204:207], v218 offset:7168
	global_load_lds_dwordx4 v184, s[42:43]
	s_add_i32 m0, s41, 0xe000
	s_nop 0
	global_load_lds_dwordx4 v186, s[42:43]
	s_waitcnt vmcnt(8)
	s_waitcnt lgkmcnt(0)
	s_barrier
	v_mfma_f32_16x16x32_bf16 v[124:127], v[128:131], v[160:163], 0
	v_mfma_f32_16x16x32_bf16 v[120:123], v[136:139], v[160:163], 0
	v_mfma_f32_16x16x32_bf16 v[108:111], v[128:131], v[168:171], 0
	v_mfma_f32_16x16x32_bf16 v[104:107], v[136:139], v[168:171], 0
	v_mfma_f32_16x16x32_bf16 v[92:95], v[128:131], v[192:195], 0
	v_mfma_f32_16x16x32_bf16 v[88:91], v[136:139], v[192:195], 0
	v_mfma_f32_16x16x32_bf16 v[76:79], v[128:131], v[200:203], 0
	v_mfma_f32_16x16x32_bf16 v[72:75], v[136:139], v[200:203], 0
	v_mfma_f32_16x16x32_bf16 v[124:127], v[132:135], v[164:167], v[124:127]
	v_mfma_f32_16x16x32_bf16 v[120:123], v[140:143], v[164:167], v[120:123]
	v_mfma_f32_16x16x32_bf16 v[108:111], v[132:135], v[172:175], v[108:111]
	v_mfma_f32_16x16x32_bf16 v[104:107], v[140:143], v[172:175], v[104:107]
	v_mfma_f32_16x16x32_bf16 v[92:95], v[132:135], v[196:199], v[92:95]
	v_mfma_f32_16x16x32_bf16 v[88:91], v[140:143], v[196:199], v[88:91]
	v_mfma_f32_16x16x32_bf16 v[76:79], v[132:135], v[204:207], v[76:79]
	v_mfma_f32_16x16x32_bf16 v[72:75], v[140:143], v[204:207], v[72:75]
	v_mfma_f32_16x16x32_bf16 v[116:119], v[144:147], v[160:163], 0
	v_mfma_f32_16x16x32_bf16 v[112:115], v[152:155], v[160:163], 0
	v_mfma_f32_16x16x32_bf16 v[100:103], v[144:147], v[168:171], 0
	v_mfma_f32_16x16x32_bf16 v[96:99], v[152:155], v[168:171], 0
	v_mfma_f32_16x16x32_bf16 v[84:87], v[144:147], v[192:195], 0
	v_mfma_f32_16x16x32_bf16 v[80:83], v[152:155], v[192:195], 0
	v_mfma_f32_16x16x32_bf16 v[68:71], v[144:147], v[200:203], 0
	v_mfma_f32_16x16x32_bf16 v[64:67], v[152:155], v[200:203], 0
	v_mfma_f32_16x16x32_bf16 v[116:119], v[148:151], v[164:167], v[116:119]
	v_mfma_f32_16x16x32_bf16 v[112:115], v[156:159], v[164:167], v[112:115]
	v_mfma_f32_16x16x32_bf16 v[100:103], v[148:151], v[172:175], v[100:103]
	v_mfma_f32_16x16x32_bf16 v[96:99], v[156:159], v[172:175], v[96:99]
	v_mfma_f32_16x16x32_bf16 v[84:87], v[148:151], v[196:199], v[84:87]
	v_mfma_f32_16x16x32_bf16 v[80:83], v[156:159], v[196:199], v[80:83]
	v_mfma_f32_16x16x32_bf16 v[68:71], v[148:151], v[204:207], v[68:71]
	v_mfma_f32_16x16x32_bf16 v[64:67], v[156:159], v[204:207], v[64:67]
	s_barrier
	s_add_i32 s59, s55, s31
	s_add_u32 s98, s44, s20
	s_addc_u32 s99, s45, s21
	s_mov_b32 m0, s59
	ds_read_b128 v[160:163], v218 offset:16384
	ds_read_b128 v[164:167], v218 offset:17408
	ds_read_b128 v[168:171], v218 offset:18432
	ds_read_b128 v[172:175], v218 offset:19456
	ds_read_b128 v[192:195], v218 offset:20480
	ds_read_b128 v[196:199], v218 offset:21504
	ds_read_b128 v[200:203], v218 offset:22528
	ds_read_b128 v[204:207], v218 offset:23552
	global_load_lds_dwordx4 v178, s[44:45]
	s_add_i32 m0, s59, 0x2000
	s_add_u32 s60, s44, 0x80000
	s_addc_u32 s61, s45, 0
	s_add_i32 s59, s56, s31
	global_load_lds_dwordx4 v182, s[44:45]
	s_mov_b32 m0, s59
	s_add_u32 s100, s46, s20
	s_addc_u32 s101, s47, s21
	global_load_lds_dwordx4 v178, s[60:61]
	s_add_i32 m0, s59, 0x2000
	s_nop 0
	global_load_lds_dwordx4 v182, s[60:61]
	s_mov_b32 m0, s41
	s_nop 0
	global_load_lds_dwordx4 v176, s[46:47]
	s_mov_b32 m0, s48
	s_nop 0
	global_load_lds_dwordx4 v180, s[46:47]
	s_waitcnt vmcnt(8)
	s_waitcnt lgkmcnt(0)
	s_barrier
	v_mfma_f32_16x16x32_bf16 v[60:63], v[128:131], v[160:163], 0
	v_mfma_f32_16x16x32_bf16 v[56:59], v[136:139], v[160:163], 0
	v_mfma_f32_16x16x32_bf16 v[44:47], v[128:131], v[168:171], 0
	v_mfma_f32_16x16x32_bf16 v[40:43], v[136:139], v[168:171], 0
	v_mfma_f32_16x16x32_bf16 v[28:31], v[128:131], v[192:195], 0
	v_mfma_f32_16x16x32_bf16 v[24:27], v[136:139], v[192:195], 0
	v_mfma_f32_16x16x32_bf16 v[12:15], v[128:131], v[200:203], 0
	v_mfma_f32_16x16x32_bf16 v[8:11], v[136:139], v[200:203], 0
	v_mfma_f32_16x16x32_bf16 v[60:63], v[132:135], v[164:167], v[60:63]
	v_mfma_f32_16x16x32_bf16 v[56:59], v[140:143], v[164:167], v[56:59]
	v_mfma_f32_16x16x32_bf16 v[44:47], v[132:135], v[172:175], v[44:47]
	v_mfma_f32_16x16x32_bf16 v[40:43], v[140:143], v[172:175], v[40:43]
	v_mfma_f32_16x16x32_bf16 v[28:31], v[132:135], v[196:199], v[28:31]
	v_mfma_f32_16x16x32_bf16 v[24:27], v[140:143], v[196:199], v[24:27]
	v_mfma_f32_16x16x32_bf16 v[12:15], v[132:135], v[204:207], v[12:15]
	v_mfma_f32_16x16x32_bf16 v[8:11], v[140:143], v[204:207], v[8:11]
	v_mfma_f32_16x16x32_bf16 v[52:55], v[144:147], v[160:163], 0
	v_mfma_f32_16x16x32_bf16 v[48:51], v[152:155], v[160:163], 0
	v_mfma_f32_16x16x32_bf16 v[36:39], v[144:147], v[168:171], 0
	v_mfma_f32_16x16x32_bf16 v[32:35], v[152:155], v[168:171], 0
	v_mfma_f32_16x16x32_bf16 v[20:23], v[144:147], v[192:195], 0
	v_mfma_f32_16x16x32_bf16 v[16:19], v[152:155], v[192:195], 0
	v_mfma_f32_16x16x32_bf16 v[4:7], v[144:147], v[200:203], 0
	v_mfma_f32_16x16x32_bf16 v[0:3], v[152:155], v[200:203], 0
	v_mfma_f32_16x16x32_bf16 v[52:55], v[148:151], v[164:167], v[52:55]
	v_mfma_f32_16x16x32_bf16 v[48:51], v[156:159], v[164:167], v[48:51]
	v_mfma_f32_16x16x32_bf16 v[36:39], v[148:151], v[172:175], v[36:39]
	v_mfma_f32_16x16x32_bf16 v[32:35], v[156:159], v[172:175], v[32:35]
	v_mfma_f32_16x16x32_bf16 v[20:23], v[148:151], v[196:199], v[20:23]
	v_mfma_f32_16x16x32_bf16 v[16:19], v[156:159], v[196:199], v[16:19]
	v_mfma_f32_16x16x32_bf16 v[4:7], v[148:151], v[204:207], v[4:7]
	v_mfma_f32_16x16x32_bf16 v[0:3], v[156:159], v[204:207], v[0:3]
	s_barrier
	s_add_i32 s59, 0, 0x18000
	s_add_i32 s60, 0, 0x1c000
	v_add_u32_e32 v140, s59, v214
	v_add_u32_e32 v156, s60, v214
	ds_read_b128 v[128:131], v140
	ds_read_b128 v[132:135], v140 offset:1024
	ds_read_b128 v[136:139], v140 offset:2048
	ds_read_b128 v[140:143], v140 offset:3072
	ds_read_b128 v[144:147], v156
	ds_read_b128 v[148:151], v156 offset:1024
	ds_read_b128 v[152:155], v156 offset:2048
	ds_read_b128 v[156:159], v156 offset:3072
	s_add_u32 s46, s46, 0x80000
	s_addc_u32 s47, s47, 0
	s_mov_b32 m0, s49
	ds_read_b128 v[160:163], v218 offset:32768
	ds_read_b128 v[164:167], v218 offset:33792
	ds_read_b128 v[168:171], v218 offset:34816
	ds_read_b128 v[172:175], v218 offset:35840
	ds_read_b128 v[192:195], v218 offset:36864
	ds_read_b128 v[196:199], v218 offset:37888
	ds_read_b128 v[200:203], v218 offset:38912
	ds_read_b128 v[204:207], v218 offset:39936
	global_load_lds_dwordx4 v176, s[46:47]
	s_mov_b32 m0, s50
	s_nop 0
	global_load_lds_dwordx4 v180, s[46:47]
	s_waitcnt vmcnt(8)
	s_waitcnt lgkmcnt(0)
	s_barrier
	v_mfma_f32_16x16x32_bf16 v[124:127], v[128:131], v[160:163], v[124:127]
	v_mfma_f32_16x16x32_bf16 v[120:123], v[136:139], v[160:163], v[120:123]
	v_mfma_f32_16x16x32_bf16 v[108:111], v[128:131], v[168:171], v[108:111]
	v_mfma_f32_16x16x32_bf16 v[104:107], v[136:139], v[168:171], v[104:107]
	v_mfma_f32_16x16x32_bf16 v[92:95], v[128:131], v[192:195], v[92:95]
	v_mfma_f32_16x16x32_bf16 v[88:91], v[136:139], v[192:195], v[88:91]
	v_mfma_f32_16x16x32_bf16 v[76:79], v[128:131], v[200:203], v[76:79]
	v_mfma_f32_16x16x32_bf16 v[72:75], v[136:139], v[200:203], v[72:75]
	v_mfma_f32_16x16x32_bf16 v[124:127], v[132:135], v[164:167], v[124:127]
	v_mfma_f32_16x16x32_bf16 v[120:123], v[140:143], v[164:167], v[120:123]
	v_mfma_f32_16x16x32_bf16 v[108:111], v[132:135], v[172:175], v[108:111]
	v_mfma_f32_16x16x32_bf16 v[104:107], v[140:143], v[172:175], v[104:107]
	v_mfma_f32_16x16x32_bf16 v[92:95], v[132:135], v[196:199], v[92:95]
	v_mfma_f32_16x16x32_bf16 v[88:91], v[140:143], v[196:199], v[88:91]
	v_mfma_f32_16x16x32_bf16 v[76:79], v[132:135], v[204:207], v[76:79]
	v_mfma_f32_16x16x32_bf16 v[72:75], v[140:143], v[204:207], v[72:75]
	v_mfma_f32_16x16x32_bf16 v[116:119], v[144:147], v[160:163], v[116:119]
	v_mfma_f32_16x16x32_bf16 v[112:115], v[152:155], v[160:163], v[112:115]
	v_mfma_f32_16x16x32_bf16 v[100:103], v[144:147], v[168:171], v[100:103]
	v_mfma_f32_16x16x32_bf16 v[96:99], v[152:155], v[168:171], v[96:99]
	v_mfma_f32_16x16x32_bf16 v[84:87], v[144:147], v[192:195], v[84:87]
	v_mfma_f32_16x16x32_bf16 v[80:83], v[152:155], v[192:195], v[80:83]
	v_mfma_f32_16x16x32_bf16 v[68:71], v[144:147], v[200:203], v[68:71]
	v_mfma_f32_16x16x32_bf16 v[64:67], v[152:155], v[200:203], v[64:67]
	v_mfma_f32_16x16x32_bf16 v[116:119], v[148:151], v[164:167], v[116:119]
	v_mfma_f32_16x16x32_bf16 v[112:115], v[156:159], v[164:167], v[112:115]
	v_mfma_f32_16x16x32_bf16 v[100:103], v[148:151], v[172:175], v[100:103]
	v_mfma_f32_16x16x32_bf16 v[96:99], v[156:159], v[172:175], v[96:99]
	v_mfma_f32_16x16x32_bf16 v[84:87], v[148:151], v[196:199], v[84:87]
	v_mfma_f32_16x16x32_bf16 v[80:83], v[156:159], v[196:199], v[80:83]
	v_mfma_f32_16x16x32_bf16 v[68:71], v[148:151], v[204:207], v[68:71]
	v_mfma_f32_16x16x32_bf16 v[64:67], v[156:159], v[204:207], v[64:67]
	s_barrier
	s_add_i32 s46, s59, s31
	s_mov_b32 m0, s46
	ds_read_b128 v[160:163], v218 offset:49152
	ds_read_b128 v[164:167], v218 offset:50176
	ds_read_b128 v[168:171], v218 offset:51200
	ds_read_b128 v[172:175], v218 offset:52224
	ds_read_b128 v[192:195], v218 offset:53248
	ds_read_b128 v[196:199], v218 offset:54272
	ds_read_b128 v[200:203], v218 offset:55296
	ds_read_b128 v[204:207], v218 offset:56320
	global_load_lds_dwordx4 v178, s[98:99]
	s_add_i32 m0, s46, 0x2000
	s_add_u32 s44, s44, 0x80080
	s_addc_u32 s45, s45, 0
	s_add_i32 s46, s60, s31
	global_load_lds_dwordx4 v182, s[98:99]
	s_mov_b32 m0, s46
	s_nop 0
	global_load_lds_dwordx4 v178, s[44:45]
	s_add_i32 m0, s46, 0x2000
	s_nop 0
	global_load_lds_dwordx4 v182, s[44:45]
	s_mov_b32 m0, s52
	s_nop 0
	global_load_lds_dwordx4 v176, s[100:101]
	s_mov_b32 m0, s53
	s_nop 0
	global_load_lds_dwordx4 v180, s[100:101]
	s_waitcnt vmcnt(8)
	s_waitcnt lgkmcnt(0)
	s_barrier
	v_mfma_f32_16x16x32_bf16 v[60:63], v[128:131], v[160:163], v[60:63]
	v_mfma_f32_16x16x32_bf16 v[56:59], v[136:139], v[160:163], v[56:59]
	v_mfma_f32_16x16x32_bf16 v[44:47], v[128:131], v[168:171], v[44:47]
	v_mfma_f32_16x16x32_bf16 v[40:43], v[136:139], v[168:171], v[40:43]
	v_mfma_f32_16x16x32_bf16 v[28:31], v[128:131], v[192:195], v[28:31]
	v_mfma_f32_16x16x32_bf16 v[24:27], v[136:139], v[192:195], v[24:27]
	v_mfma_f32_16x16x32_bf16 v[12:15], v[128:131], v[200:203], v[12:15]
	v_mfma_f32_16x16x32_bf16 v[8:11], v[136:139], v[200:203], v[8:11]
	v_mfma_f32_16x16x32_bf16 v[60:63], v[132:135], v[164:167], v[60:63]
	v_mfma_f32_16x16x32_bf16 v[56:59], v[140:143], v[164:167], v[56:59]
	v_mfma_f32_16x16x32_bf16 v[44:47], v[132:135], v[172:175], v[44:47]
	v_mfma_f32_16x16x32_bf16 v[40:43], v[140:143], v[172:175], v[40:43]
	v_mfma_f32_16x16x32_bf16 v[28:31], v[132:135], v[196:199], v[28:31]
	v_mfma_f32_16x16x32_bf16 v[24:27], v[140:143], v[196:199], v[24:27]
	v_mfma_f32_16x16x32_bf16 v[12:15], v[132:135], v[204:207], v[12:15]
	v_mfma_f32_16x16x32_bf16 v[8:11], v[140:143], v[204:207], v[8:11]
	v_mfma_f32_16x16x32_bf16 v[52:55], v[144:147], v[160:163], v[52:55]
	v_mfma_f32_16x16x32_bf16 v[48:51], v[152:155], v[160:163], v[48:51]
	v_mfma_f32_16x16x32_bf16 v[36:39], v[144:147], v[168:171], v[36:39]
	v_mfma_f32_16x16x32_bf16 v[32:35], v[152:155], v[168:171], v[32:35]
	v_mfma_f32_16x16x32_bf16 v[20:23], v[144:147], v[192:195], v[20:23]
	v_mfma_f32_16x16x32_bf16 v[16:19], v[152:155], v[192:195], v[16:19]
	v_mfma_f32_16x16x32_bf16 v[4:7], v[144:147], v[200:203], v[4:7]
	v_mfma_f32_16x16x32_bf16 v[0:3], v[152:155], v[200:203], v[0:3]
	v_mfma_f32_16x16x32_bf16 v[52:55], v[148:151], v[164:167], v[52:55]
	v_mfma_f32_16x16x32_bf16 v[48:51], v[156:159], v[164:167], v[48:51]
	v_mfma_f32_16x16x32_bf16 v[36:39], v[148:151], v[172:175], v[36:39]
	v_mfma_f32_16x16x32_bf16 v[32:35], v[156:159], v[172:175], v[32:35]
	v_mfma_f32_16x16x32_bf16 v[20:23], v[148:151], v[196:199], v[20:23]
	v_mfma_f32_16x16x32_bf16 v[16:19], v[156:159], v[196:199], v[16:19]
	v_mfma_f32_16x16x32_bf16 v[4:7], v[148:151], v[204:207], v[4:7]
	v_mfma_f32_16x16x32_bf16 v[0:3], v[156:159], v[204:207], v[0:3]
	s_barrier
	s_add_i32 s58, s58, 2
	s_add_u32 s42, s42, 0x100
	s_addc_u32 s43, s43, 0
	s_add_u32 s25, s25, 0x100
	s_addc_u32 s35, s35, 0
	s_cmp_gt_u32 s58, 29
.LBB0_543:
	ds_read_b128 v[128:131], v216
	ds_read_b128 v[132:135], v216 offset:1024
	ds_read_b128 v[136:139], v216 offset:2048
	ds_read_b128 v[140:143], v216 offset:3072
	ds_read_b128 v[144:147], v217
	ds_read_b128 v[148:151], v217 offset:1024
	ds_read_b128 v[152:155], v217 offset:2048
	ds_read_b128 v[156:159], v217 offset:3072
	s_add_u32 s44, s42, 0xfff80080
	s_addc_u32 s45, s43, -1
	s_cmp_eq_u32 s58, 28
	s_cselect_b32 s47, s0, s45
	s_cselect_b32 s46, s1, s44
	s_cselect_b32 s45, s3, s35
	s_cselect_b32 s44, s9, s25
	s_add_i32 m0, s41, 0xc000
	ds_read_b128 v[160:163], v218
	ds_read_b128 v[164:167], v218 offset:1024
	ds_read_b128 v[168:171], v218 offset:2048
	ds_read_b128 v[172:175], v218 offset:3072
	ds_read_b128 v[192:195], v218 offset:4096
	ds_read_b128 v[196:199], v218 offset:5120
	ds_read_b128 v[200:203], v218 offset:6144
	ds_read_b128 v[204:207], v218 offset:7168
	global_load_lds_dwordx4 v184, s[42:43]
	s_add_i32 m0, s41, 0xe000
	s_nop 0
	global_load_lds_dwordx4 v186, s[42:43]
	s_waitcnt vmcnt(8)
	s_waitcnt lgkmcnt(0)
	s_barrier
	v_mfma_f32_16x16x32_bf16 v[124:127], v[128:131], v[160:163], v[124:127]
	v_mfma_f32_16x16x32_bf16 v[120:123], v[136:139], v[160:163], v[120:123]
	v_mfma_f32_16x16x32_bf16 v[108:111], v[128:131], v[168:171], v[108:111]
	v_mfma_f32_16x16x32_bf16 v[104:107], v[136:139], v[168:171], v[104:107]
	v_mfma_f32_16x16x32_bf16 v[92:95], v[128:131], v[192:195], v[92:95]
	v_mfma_f32_16x16x32_bf16 v[88:91], v[136:139], v[192:195], v[88:91]
	v_mfma_f32_16x16x32_bf16 v[76:79], v[128:131], v[200:203], v[76:79]
	v_mfma_f32_16x16x32_bf16 v[72:75], v[136:139], v[200:203], v[72:75]
	v_mfma_f32_16x16x32_bf16 v[124:127], v[132:135], v[164:167], v[124:127]
	v_mfma_f32_16x16x32_bf16 v[120:123], v[140:143], v[164:167], v[120:123]
	v_mfma_f32_16x16x32_bf16 v[108:111], v[132:135], v[172:175], v[108:111]
	v_mfma_f32_16x16x32_bf16 v[104:107], v[140:143], v[172:175], v[104:107]
	v_mfma_f32_16x16x32_bf16 v[92:95], v[132:135], v[196:199], v[92:95]
	v_mfma_f32_16x16x32_bf16 v[88:91], v[140:143], v[196:199], v[88:91]
	v_mfma_f32_16x16x32_bf16 v[76:79], v[132:135], v[204:207], v[76:79]
	v_mfma_f32_16x16x32_bf16 v[72:75], v[140:143], v[204:207], v[72:75]
	v_mfma_f32_16x16x32_bf16 v[116:119], v[144:147], v[160:163], v[116:119]
	v_mfma_f32_16x16x32_bf16 v[112:115], v[152:155], v[160:163], v[112:115]
	v_mfma_f32_16x16x32_bf16 v[100:103], v[144:147], v[168:171], v[100:103]
	v_mfma_f32_16x16x32_bf16 v[96:99], v[152:155], v[168:171], v[96:99]
	v_mfma_f32_16x16x32_bf16 v[84:87], v[144:147], v[192:195], v[84:87]
	v_mfma_f32_16x16x32_bf16 v[80:83], v[152:155], v[192:195], v[80:83]
	v_mfma_f32_16x16x32_bf16 v[68:71], v[144:147], v[200:203], v[68:71]
	v_mfma_f32_16x16x32_bf16 v[64:67], v[152:155], v[200:203], v[64:67]
	v_mfma_f32_16x16x32_bf16 v[116:119], v[148:151], v[164:167], v[116:119]
	v_mfma_f32_16x16x32_bf16 v[112:115], v[156:159], v[164:167], v[112:115]
	v_mfma_f32_16x16x32_bf16 v[100:103], v[148:151], v[172:175], v[100:103]
	v_mfma_f32_16x16x32_bf16 v[96:99], v[156:159], v[172:175], v[96:99]
	v_mfma_f32_16x16x32_bf16 v[84:87], v[148:151], v[196:199], v[84:87]
	v_mfma_f32_16x16x32_bf16 v[80:83], v[156:159], v[196:199], v[80:83]
	v_mfma_f32_16x16x32_bf16 v[68:71], v[148:151], v[204:207], v[68:71]
	v_mfma_f32_16x16x32_bf16 v[64:67], v[156:159], v[204:207], v[64:67]
	s_barrier
	s_add_i32 s59, s55, s31
	s_add_u32 s98, s44, s20
	s_addc_u32 s99, s45, s21
	s_mov_b32 m0, s59
	ds_read_b128 v[160:163], v218 offset:16384
	ds_read_b128 v[164:167], v218 offset:17408
	ds_read_b128 v[168:171], v218 offset:18432
	ds_read_b128 v[172:175], v218 offset:19456
	ds_read_b128 v[192:195], v218 offset:20480
	ds_read_b128 v[196:199], v218 offset:21504
	ds_read_b128 v[200:203], v218 offset:22528
	ds_read_b128 v[204:207], v218 offset:23552
	global_load_lds_dwordx4 v178, s[44:45]
	s_add_i32 m0, s59, 0x2000
	s_add_u32 s60, s44, 0x80000
	s_addc_u32 s61, s45, 0
	s_add_i32 s59, s56, s31
	global_load_lds_dwordx4 v182, s[44:45]
	s_mov_b32 m0, s59
	s_add_u32 s100, s46, s20
	s_addc_u32 s101, s47, s21
	global_load_lds_dwordx4 v178, s[60:61]
	s_add_i32 m0, s59, 0x2000
	s_nop 0
	global_load_lds_dwordx4 v182, s[60:61]
	s_mov_b32 m0, s41
	s_nop 0
	global_load_lds_dwordx4 v176, s[46:47]
	s_mov_b32 m0, s48
	s_nop 0
	global_load_lds_dwordx4 v180, s[46:47]
	s_waitcnt vmcnt(8)
	s_waitcnt lgkmcnt(0)
	s_barrier
	v_mfma_f32_16x16x32_bf16 v[60:63], v[128:131], v[160:163], v[60:63]
	v_mfma_f32_16x16x32_bf16 v[56:59], v[136:139], v[160:163], v[56:59]
	v_mfma_f32_16x16x32_bf16 v[44:47], v[128:131], v[168:171], v[44:47]
	v_mfma_f32_16x16x32_bf16 v[40:43], v[136:139], v[168:171], v[40:43]
	v_mfma_f32_16x16x32_bf16 v[28:31], v[128:131], v[192:195], v[28:31]
	v_mfma_f32_16x16x32_bf16 v[24:27], v[136:139], v[192:195], v[24:27]
	v_mfma_f32_16x16x32_bf16 v[12:15], v[128:131], v[200:203], v[12:15]
	v_mfma_f32_16x16x32_bf16 v[8:11], v[136:139], v[200:203], v[8:11]
	v_mfma_f32_16x16x32_bf16 v[60:63], v[132:135], v[164:167], v[60:63]
	v_mfma_f32_16x16x32_bf16 v[56:59], v[140:143], v[164:167], v[56:59]
	v_mfma_f32_16x16x32_bf16 v[44:47], v[132:135], v[172:175], v[44:47]
	v_mfma_f32_16x16x32_bf16 v[40:43], v[140:143], v[172:175], v[40:43]
	v_mfma_f32_16x16x32_bf16 v[28:31], v[132:135], v[196:199], v[28:31]
	v_mfma_f32_16x16x32_bf16 v[24:27], v[140:143], v[196:199], v[24:27]
	v_mfma_f32_16x16x32_bf16 v[12:15], v[132:135], v[204:207], v[12:15]
	v_mfma_f32_16x16x32_bf16 v[8:11], v[140:143], v[204:207], v[8:11]
	v_mfma_f32_16x16x32_bf16 v[52:55], v[144:147], v[160:163], v[52:55]
	v_mfma_f32_16x16x32_bf16 v[48:51], v[152:155], v[160:163], v[48:51]
	v_mfma_f32_16x16x32_bf16 v[36:39], v[144:147], v[168:171], v[36:39]
	v_mfma_f32_16x16x32_bf16 v[32:35], v[152:155], v[168:171], v[32:35]
	v_mfma_f32_16x16x32_bf16 v[20:23], v[144:147], v[192:195], v[20:23]
	v_mfma_f32_16x16x32_bf16 v[16:19], v[152:155], v[192:195], v[16:19]
	v_mfma_f32_16x16x32_bf16 v[4:7], v[144:147], v[200:203], v[4:7]
	v_mfma_f32_16x16x32_bf16 v[0:3], v[152:155], v[200:203], v[0:3]
	v_mfma_f32_16x16x32_bf16 v[52:55], v[148:151], v[164:167], v[52:55]
	v_mfma_f32_16x16x32_bf16 v[48:51], v[156:159], v[164:167], v[48:51]
	v_mfma_f32_16x16x32_bf16 v[36:39], v[148:151], v[172:175], v[36:39]
	v_mfma_f32_16x16x32_bf16 v[32:35], v[156:159], v[172:175], v[32:35]
	v_mfma_f32_16x16x32_bf16 v[20:23], v[148:151], v[196:199], v[20:23]
	v_mfma_f32_16x16x32_bf16 v[16:19], v[156:159], v[196:199], v[16:19]
	v_mfma_f32_16x16x32_bf16 v[4:7], v[148:151], v[204:207], v[4:7]
	v_mfma_f32_16x16x32_bf16 v[0:3], v[156:159], v[204:207], v[0:3]
	s_barrier
	s_add_i32 s59, 0, 0x18000
	s_add_i32 s60, 0, 0x1c000
	v_add_u32_e32 v140, s59, v214
	v_add_u32_e32 v156, s60, v214
	ds_read_b128 v[128:131], v140
	ds_read_b128 v[132:135], v140 offset:1024
	ds_read_b128 v[136:139], v140 offset:2048
	ds_read_b128 v[140:143], v140 offset:3072
	ds_read_b128 v[144:147], v156
	ds_read_b128 v[148:151], v156 offset:1024
	ds_read_b128 v[152:155], v156 offset:2048
	ds_read_b128 v[156:159], v156 offset:3072
	s_add_u32 s46, s46, 0x80000
	s_addc_u32 s47, s47, 0
	s_mov_b32 m0, s49
	ds_read_b128 v[160:163], v218 offset:32768
	ds_read_b128 v[164:167], v218 offset:33792
	ds_read_b128 v[168:171], v218 offset:34816
	ds_read_b128 v[172:175], v218 offset:35840
	ds_read_b128 v[192:195], v218 offset:36864
	ds_read_b128 v[196:199], v218 offset:37888
	ds_read_b128 v[200:203], v218 offset:38912
	ds_read_b128 v[204:207], v218 offset:39936
	global_load_lds_dwordx4 v176, s[46:47]
	s_mov_b32 m0, s50
	s_nop 0
	global_load_lds_dwordx4 v180, s[46:47]
	s_waitcnt vmcnt(8)
	s_waitcnt lgkmcnt(0)
	s_barrier
	v_mfma_f32_16x16x32_bf16 v[124:127], v[128:131], v[160:163], v[124:127]
	v_mfma_f32_16x16x32_bf16 v[120:123], v[136:139], v[160:163], v[120:123]
	v_mfma_f32_16x16x32_bf16 v[108:111], v[128:131], v[168:171], v[108:111]
	v_mfma_f32_16x16x32_bf16 v[104:107], v[136:139], v[168:171], v[104:107]
	v_mfma_f32_16x16x32_bf16 v[92:95], v[128:131], v[192:195], v[92:95]
	v_mfma_f32_16x16x32_bf16 v[88:91], v[136:139], v[192:195], v[88:91]
	v_mfma_f32_16x16x32_bf16 v[76:79], v[128:131], v[200:203], v[76:79]
	v_mfma_f32_16x16x32_bf16 v[72:75], v[136:139], v[200:203], v[72:75]
	v_mfma_f32_16x16x32_bf16 v[124:127], v[132:135], v[164:167], v[124:127]
	v_mfma_f32_16x16x32_bf16 v[120:123], v[140:143], v[164:167], v[120:123]
	v_mfma_f32_16x16x32_bf16 v[108:111], v[132:135], v[172:175], v[108:111]
	v_mfma_f32_16x16x32_bf16 v[104:107], v[140:143], v[172:175], v[104:107]
	v_mfma_f32_16x16x32_bf16 v[92:95], v[132:135], v[196:199], v[92:95]
	v_mfma_f32_16x16x32_bf16 v[88:91], v[140:143], v[196:199], v[88:91]
	v_mfma_f32_16x16x32_bf16 v[76:79], v[132:135], v[204:207], v[76:79]
	v_mfma_f32_16x16x32_bf16 v[72:75], v[140:143], v[204:207], v[72:75]
	v_mfma_f32_16x16x32_bf16 v[116:119], v[144:147], v[160:163], v[116:119]
	v_mfma_f32_16x16x32_bf16 v[112:115], v[152:155], v[160:163], v[112:115]
	v_mfma_f32_16x16x32_bf16 v[100:103], v[144:147], v[168:171], v[100:103]
	v_mfma_f32_16x16x32_bf16 v[96:99], v[152:155], v[168:171], v[96:99]
	v_mfma_f32_16x16x32_bf16 v[84:87], v[144:147], v[192:195], v[84:87]
	v_mfma_f32_16x16x32_bf16 v[80:83], v[152:155], v[192:195], v[80:83]
	v_mfma_f32_16x16x32_bf16 v[68:71], v[144:147], v[200:203], v[68:71]
	v_mfma_f32_16x16x32_bf16 v[64:67], v[152:155], v[200:203], v[64:67]
	v_mfma_f32_16x16x32_bf16 v[116:119], v[148:151], v[164:167], v[116:119]
	v_mfma_f32_16x16x32_bf16 v[112:115], v[156:159], v[164:167], v[112:115]
	v_mfma_f32_16x16x32_bf16 v[100:103], v[148:151], v[172:175], v[100:103]
	v_mfma_f32_16x16x32_bf16 v[96:99], v[156:159], v[172:175], v[96:99]
	v_mfma_f32_16x16x32_bf16 v[84:87], v[148:151], v[196:199], v[84:87]
	v_mfma_f32_16x16x32_bf16 v[80:83], v[156:159], v[196:199], v[80:83]
	v_mfma_f32_16x16x32_bf16 v[68:71], v[148:151], v[204:207], v[68:71]
	v_mfma_f32_16x16x32_bf16 v[64:67], v[156:159], v[204:207], v[64:67]
	s_barrier
	s_add_i32 s46, s59, s31
	s_mov_b32 m0, s46
	ds_read_b128 v[160:163], v218 offset:49152
	ds_read_b128 v[164:167], v218 offset:50176
	ds_read_b128 v[168:171], v218 offset:51200
	ds_read_b128 v[172:175], v218 offset:52224
	ds_read_b128 v[192:195], v218 offset:53248
	ds_read_b128 v[196:199], v218 offset:54272
	ds_read_b128 v[200:203], v218 offset:55296
	ds_read_b128 v[204:207], v218 offset:56320
	global_load_lds_dwordx4 v178, s[98:99]
	s_add_i32 m0, s46, 0x2000
	s_add_u32 s44, s44, 0x80080
	s_addc_u32 s45, s45, 0
	s_add_i32 s46, s60, s31
	global_load_lds_dwordx4 v182, s[98:99]
	s_mov_b32 m0, s46
	s_nop 0
	global_load_lds_dwordx4 v178, s[44:45]
	s_add_i32 m0, s46, 0x2000
	s_nop 0
	global_load_lds_dwordx4 v182, s[44:45]
	s_mov_b32 m0, s52
	s_nop 0
	global_load_lds_dwordx4 v176, s[100:101]
	s_mov_b32 m0, s53
	s_nop 0
	global_load_lds_dwordx4 v180, s[100:101]
	s_waitcnt vmcnt(8)
	s_waitcnt lgkmcnt(0)
	s_barrier
	v_mfma_f32_16x16x32_bf16 v[60:63], v[128:131], v[160:163], v[60:63]
	v_mfma_f32_16x16x32_bf16 v[56:59], v[136:139], v[160:163], v[56:59]
	v_mfma_f32_16x16x32_bf16 v[44:47], v[128:131], v[168:171], v[44:47]
	v_mfma_f32_16x16x32_bf16 v[40:43], v[136:139], v[168:171], v[40:43]
	v_mfma_f32_16x16x32_bf16 v[28:31], v[128:131], v[192:195], v[28:31]
	v_mfma_f32_16x16x32_bf16 v[24:27], v[136:139], v[192:195], v[24:27]
	v_mfma_f32_16x16x32_bf16 v[12:15], v[128:131], v[200:203], v[12:15]
	v_mfma_f32_16x16x32_bf16 v[8:11], v[136:139], v[200:203], v[8:11]
	v_mfma_f32_16x16x32_bf16 v[60:63], v[132:135], v[164:167], v[60:63]
	v_mfma_f32_16x16x32_bf16 v[56:59], v[140:143], v[164:167], v[56:59]
	v_mfma_f32_16x16x32_bf16 v[44:47], v[132:135], v[172:175], v[44:47]
	v_mfma_f32_16x16x32_bf16 v[40:43], v[140:143], v[172:175], v[40:43]
	v_mfma_f32_16x16x32_bf16 v[28:31], v[132:135], v[196:199], v[28:31]
	v_mfma_f32_16x16x32_bf16 v[24:27], v[140:143], v[196:199], v[24:27]
	v_mfma_f32_16x16x32_bf16 v[12:15], v[132:135], v[204:207], v[12:15]
	v_mfma_f32_16x16x32_bf16 v[8:11], v[140:143], v[204:207], v[8:11]
	v_mfma_f32_16x16x32_bf16 v[52:55], v[144:147], v[160:163], v[52:55]
	v_mfma_f32_16x16x32_bf16 v[48:51], v[152:155], v[160:163], v[48:51]
	v_mfma_f32_16x16x32_bf16 v[36:39], v[144:147], v[168:171], v[36:39]
	v_mfma_f32_16x16x32_bf16 v[32:35], v[152:155], v[168:171], v[32:35]
	v_mfma_f32_16x16x32_bf16 v[20:23], v[144:147], v[192:195], v[20:23]
	v_mfma_f32_16x16x32_bf16 v[16:19], v[152:155], v[192:195], v[16:19]
	v_mfma_f32_16x16x32_bf16 v[4:7], v[144:147], v[200:203], v[4:7]
	v_mfma_f32_16x16x32_bf16 v[0:3], v[152:155], v[200:203], v[0:3]
	v_mfma_f32_16x16x32_bf16 v[52:55], v[148:151], v[164:167], v[52:55]
	v_mfma_f32_16x16x32_bf16 v[48:51], v[156:159], v[164:167], v[48:51]
	v_mfma_f32_16x16x32_bf16 v[36:39], v[148:151], v[172:175], v[36:39]
	v_mfma_f32_16x16x32_bf16 v[32:35], v[156:159], v[172:175], v[32:35]
	v_mfma_f32_16x16x32_bf16 v[20:23], v[148:151], v[196:199], v[20:23]
	v_mfma_f32_16x16x32_bf16 v[16:19], v[156:159], v[196:199], v[16:19]
	v_mfma_f32_16x16x32_bf16 v[4:7], v[148:151], v[204:207], v[4:7]
	v_mfma_f32_16x16x32_bf16 v[0:3], v[156:159], v[204:207], v[0:3]
	s_barrier
	s_add_i32 s58, s58, 2
	s_add_u32 s42, s42, 0x100
	s_addc_u32 s43, s43, 0
	s_add_u32 s25, s25, 0x100
	s_addc_u32 s35, s35, 0
	s_cmp_gt_u32 s58, 29
	s_cbranch_scc0 .LBB0_543
	s_setprio 0
	s_and_b64 vcc, exec, s[22:23]
	s_cbranch_vccz .LBB0_546
	s_barrier

.LBB0_635:
	s_ashr_i32 s67, s66, 31
	s_lshl_b64 s[12:13], s[66:67], 20
	s_add_u32 s70, s55, s12
	s_addc_u32 s71, s57, s13
	s_and_b64 s[6:7], s[6:7], exec
	s_cselect_b32 s1, s71, s11
	s_cselect_b32 s3, s70, s10
	s_add_u32 s6, s8, 0x80080
	s_addc_u32 s7, s9, 0
	s_add_u32 s12, s10, 0x100
	s_addc_u32 s13, s11, 0
	s_mov_b32 s15, -2
	s_waitcnt vmcnt(0)
	s_cmp_ge_u32 s97, 0x100
	s_cbranch_scc0 .Lkprio_2
	s_setprio 1
.Lkprio_2:
	ds_read_b128 v[148:151], v197
	ds_read_b128 v[170:173], v197 offset:1024
	ds_read_b128 v[174:177], v197 offset:2048
	ds_read_b128 v[178:181], v197 offset:3072
	ds_read_b128 v[182:185], v198
	ds_read_b128 v[186:189], v198 offset:1024
	ds_read_b128 v[202:205], v198 offset:2048
	ds_read_b128 v[206:209], v198 offset:3072
	s_add_u32 s8, s6, 0xfff80080
	s_addc_u32 s9, s7, -1
	s_cmp_eq_u32 s15, 28
	s_cselect_b32 s11, s69, s9
	s_cselect_b32 s10, s68, s8
	s_cselect_b32 s9, s1, s13
	s_cselect_b32 s8, s3, s12
	s_add_i32 m0, s72, 0xc000
	ds_read_b128 v[214:217], v199
	ds_read_b128 v[218:221], v199 offset:1024
	ds_read_b128 v[222:225], v199 offset:2048
	ds_read_b128 v[226:229], v199 offset:3072
	ds_read_b128 v[230:233], v199 offset:4096
	ds_read_b128 v[234:237], v199 offset:5120
	ds_read_b128 v[238:241], v199 offset:6144
	ds_read_b128 v[242:245], v199 offset:7168
	global_load_lds_dwordx4 v162, s[6:7]
	s_add_i32 m0, s72, 0xe000
	s_nop 0
	global_load_lds_dwordx4 v164, s[6:7]
	s_waitcnt vmcnt(8)
	s_waitcnt lgkmcnt(0)
	s_barrier
	v_mfma_f32_16x16x32_bf16 v[112:115], v[148:151], v[214:217], 0
	v_mfma_f32_16x16x32_bf16 v[80:83], v[174:177], v[214:217], 0
	v_mfma_f32_16x16x32_bf16 v[116:119], v[148:151], v[222:225], 0
	v_mfma_f32_16x16x32_bf16 v[88:91], v[174:177], v[222:225], 0
	v_mfma_f32_16x16x32_bf16 v[124:127], v[148:151], v[230:233], 0
	v_mfma_f32_16x16x32_bf16 v[92:95], v[174:177], v[230:233], 0
	v_mfma_f32_16x16x32_bf16 v[120:123], v[148:151], v[238:241], 0
	v_mfma_f32_16x16x32_bf16 v[84:87], v[174:177], v[238:241], 0
	v_mfma_f32_16x16x32_bf16 v[112:115], v[170:173], v[218:221], v[112:115]
	v_mfma_f32_16x16x32_bf16 v[80:83], v[178:181], v[218:221], v[80:83]
	v_mfma_f32_16x16x32_bf16 v[116:119], v[170:173], v[226:229], v[116:119]
	v_mfma_f32_16x16x32_bf16 v[88:91], v[178:181], v[226:229], v[88:91]
	v_mfma_f32_16x16x32_bf16 v[124:127], v[170:173], v[234:237], v[124:127]
	v_mfma_f32_16x16x32_bf16 v[92:95], v[178:181], v[234:237], v[92:95]
	v_mfma_f32_16x16x32_bf16 v[120:123], v[170:173], v[242:245], v[120:123]
	v_mfma_f32_16x16x32_bf16 v[84:87], v[178:181], v[242:245], v[84:87]
	v_mfma_f32_16x16x32_bf16 v[108:111], v[182:185], v[214:217], 0
	v_mfma_f32_16x16x32_bf16 v[76:79], v[202:205], v[214:217], 0
	v_mfma_f32_16x16x32_bf16 v[104:107], v[182:185], v[222:225], 0
	v_mfma_f32_16x16x32_bf16 v[72:75], v[202:205], v[222:225], 0
	v_mfma_f32_16x16x32_bf16 v[100:103], v[182:185], v[230:233], 0
	v_mfma_f32_16x16x32_bf16 v[68:71], v[202:205], v[230:233], 0
	v_mfma_f32_16x16x32_bf16 v[96:99], v[182:185], v[238:241], 0
	v_mfma_f32_16x16x32_bf16 v[64:67], v[202:205], v[238:241], 0
	v_mfma_f32_16x16x32_bf16 v[108:111], v[186:189], v[218:221], v[108:111]
	v_mfma_f32_16x16x32_bf16 v[76:79], v[206:209], v[218:221], v[76:79]
	v_mfma_f32_16x16x32_bf16 v[104:107], v[186:189], v[226:229], v[104:107]
	v_mfma_f32_16x16x32_bf16 v[72:75], v[206:209], v[226:229], v[72:75]
	v_mfma_f32_16x16x32_bf16 v[100:103], v[186:189], v[234:237], v[100:103]
	v_mfma_f32_16x16x32_bf16 v[68:71], v[206:209], v[234:237], v[68:71]
	v_mfma_f32_16x16x32_bf16 v[96:99], v[186:189], v[242:245], v[96:99]
	v_mfma_f32_16x16x32_bf16 v[64:67], v[206:209], v[242:245], v[64:67]
	s_barrier
	s_add_i32 s16, s94, s63
	s_add_u32 s98, s8, s40
	s_addc_u32 s99, s9, s41
	s_mov_b32 m0, s16
	ds_read_b128 v[214:217], v199 offset:16384
	ds_read_b128 v[218:221], v199 offset:17408
	ds_read_b128 v[222:225], v199 offset:18432
	ds_read_b128 v[226:229], v199 offset:19456
	ds_read_b128 v[230:233], v199 offset:20480
	ds_read_b128 v[234:237], v199 offset:21504
	ds_read_b128 v[238:241], v199 offset:22528
	ds_read_b128 v[242:245], v199 offset:23552
	global_load_lds_dwordx4 v154, s[8:9]
	s_add_i32 m0, s16, 0x2000
	s_add_u32 s16, s8, 0x80000
	s_addc_u32 s17, s9, 0
	s_add_i32 s18, s95, s63
	global_load_lds_dwordx4 v158, s[8:9]
	s_mov_b32 m0, s18
	s_add_u32 s100, s10, s40
	s_addc_u32 s101, s11, s41
	global_load_lds_dwordx4 v154, s[16:17]
	s_add_i32 m0, s18, 0x2000
	s_nop 0
	global_load_lds_dwordx4 v158, s[16:17]
	s_mov_b32 m0, s72
	s_nop 0
	global_load_lds_dwordx4 v152, s[10:11]
	s_mov_b32 m0, s73
	s_nop 0
	global_load_lds_dwordx4 v156, s[10:11]
	s_waitcnt vmcnt(8)
	s_waitcnt lgkmcnt(0)
	s_barrier
	v_mfma_f32_16x16x32_bf16 v[48:51], v[148:151], v[214:217], 0
	v_mfma_f32_16x16x32_bf16 v[16:19], v[174:177], v[214:217], 0
	v_mfma_f32_16x16x32_bf16 v[52:55], v[148:151], v[222:225], 0
	v_mfma_f32_16x16x32_bf16 v[24:27], v[174:177], v[222:225], 0
	v_mfma_f32_16x16x32_bf16 v[60:63], v[148:151], v[230:233], 0
	v_mfma_f32_16x16x32_bf16 v[28:31], v[174:177], v[230:233], 0
	v_mfma_f32_16x16x32_bf16 v[56:59], v[148:151], v[238:241], 0
	v_mfma_f32_16x16x32_bf16 v[20:23], v[174:177], v[238:241], 0
	v_mfma_f32_16x16x32_bf16 v[48:51], v[170:173], v[218:221], v[48:51]
	v_mfma_f32_16x16x32_bf16 v[16:19], v[178:181], v[218:221], v[16:19]
	v_mfma_f32_16x16x32_bf16 v[52:55], v[170:173], v[226:229], v[52:55]
	v_mfma_f32_16x16x32_bf16 v[24:27], v[178:181], v[226:229], v[24:27]
	v_mfma_f32_16x16x32_bf16 v[60:63], v[170:173], v[234:237], v[60:63]
	v_mfma_f32_16x16x32_bf16 v[28:31], v[178:181], v[234:237], v[28:31]
	v_mfma_f32_16x16x32_bf16 v[56:59], v[170:173], v[242:245], v[56:59]
	v_mfma_f32_16x16x32_bf16 v[20:23], v[178:181], v[242:245], v[20:23]
	v_mfma_f32_16x16x32_bf16 v[44:47], v[182:185], v[214:217], 0
	v_mfma_f32_16x16x32_bf16 v[12:15], v[202:205], v[214:217], 0
	v_mfma_f32_16x16x32_bf16 v[40:43], v[182:185], v[222:225], 0
	v_mfma_f32_16x16x32_bf16 v[8:11], v[202:205], v[222:225], 0
	v_mfma_f32_16x16x32_bf16 v[36:39], v[182:185], v[230:233], 0
	v_mfma_f32_16x16x32_bf16 v[4:7], v[202:205], v[230:233], 0
	v_mfma_f32_16x16x32_bf16 v[32:35], v[182:185], v[238:241], 0
	v_mfma_f32_16x16x32_bf16 v[0:3], v[202:205], v[238:241], 0
	v_mfma_f32_16x16x32_bf16 v[44:47], v[186:189], v[218:221], v[44:47]
	v_mfma_f32_16x16x32_bf16 v[12:15], v[206:209], v[218:221], v[12:15]
	v_mfma_f32_16x16x32_bf16 v[40:43], v[186:189], v[226:229], v[40:43]
	v_mfma_f32_16x16x32_bf16 v[8:11], v[206:209], v[226:229], v[8:11]
	v_mfma_f32_16x16x32_bf16 v[36:39], v[186:189], v[234:237], v[36:39]
	v_mfma_f32_16x16x32_bf16 v[4:7], v[206:209], v[234:237], v[4:7]
	v_mfma_f32_16x16x32_bf16 v[32:35], v[186:189], v[242:245], v[32:35]
	v_mfma_f32_16x16x32_bf16 v[0:3], v[206:209], v[242:245], v[0:3]
	s_barrier
	s_add_i32 s16, 0, 0x18000
	s_add_i32 s17, 0, 0x1c000
	v_add_u32_e32 v178, s16, v196
	v_add_u32_e32 v201, s17, v196
	ds_read_b128 v[148:151], v178
	ds_read_b128 v[170:173], v178 offset:1024
	ds_read_b128 v[174:177], v178 offset:2048
	ds_read_b128 v[178:181], v178 offset:3072
	ds_read_b128 v[182:185], v201
	ds_read_b128 v[186:189], v201 offset:1024
	ds_read_b128 v[202:205], v201 offset:2048
	ds_read_b128 v[206:209], v201 offset:3072
	s_add_u32 s10, s10, 0x80000
	s_addc_u32 s11, s11, 0
	s_mov_b32 m0, s74
	ds_read_b128 v[214:217], v199 offset:32768
	ds_read_b128 v[218:221], v199 offset:33792
	ds_read_b128 v[222:225], v199 offset:34816
	ds_read_b128 v[226:229], v199 offset:35840
	ds_read_b128 v[230:233], v199 offset:36864
	ds_read_b128 v[234:237], v199 offset:37888
	ds_read_b128 v[238:241], v199 offset:38912
	ds_read_b128 v[242:245], v199 offset:39936
	global_load_lds_dwordx4 v152, s[10:11]
	s_mov_b32 m0, s75
	s_nop 0
	global_load_lds_dwordx4 v156, s[10:11]
	s_waitcnt vmcnt(8)
	s_waitcnt lgkmcnt(0)
	s_barrier
	v_mfma_f32_16x16x32_bf16 v[112:115], v[148:151], v[214:217], v[112:115]
	v_mfma_f32_16x16x32_bf16 v[80:83], v[174:177], v[214:217], v[80:83]
	v_mfma_f32_16x16x32_bf16 v[116:119], v[148:151], v[222:225], v[116:119]
	v_mfma_f32_16x16x32_bf16 v[88:91], v[174:177], v[222:225], v[88:91]
	v_mfma_f32_16x16x32_bf16 v[124:127], v[148:151], v[230:233], v[124:127]
	v_mfma_f32_16x16x32_bf16 v[92:95], v[174:177], v[230:233], v[92:95]
	v_mfma_f32_16x16x32_bf16 v[120:123], v[148:151], v[238:241], v[120:123]
	v_mfma_f32_16x16x32_bf16 v[84:87], v[174:177], v[238:241], v[84:87]
	v_mfma_f32_16x16x32_bf16 v[112:115], v[170:173], v[218:221], v[112:115]
	v_mfma_f32_16x16x32_bf16 v[80:83], v[178:181], v[218:221], v[80:83]
	v_mfma_f32_16x16x32_bf16 v[116:119], v[170:173], v[226:229], v[116:119]
	v_mfma_f32_16x16x32_bf16 v[88:91], v[178:181], v[226:229], v[88:91]
	v_mfma_f32_16x16x32_bf16 v[124:127], v[170:173], v[234:237], v[124:127]
	v_mfma_f32_16x16x32_bf16 v[92:95], v[178:181], v[234:237], v[92:95]
	v_mfma_f32_16x16x32_bf16 v[120:123], v[170:173], v[242:245], v[120:123]
	v_mfma_f32_16x16x32_bf16 v[84:87], v[178:181], v[242:245], v[84:87]
	v_mfma_f32_16x16x32_bf16 v[108:111], v[182:185], v[214:217], v[108:111]
	v_mfma_f32_16x16x32_bf16 v[76:79], v[202:205], v[214:217], v[76:79]
	v_mfma_f32_16x16x32_bf16 v[104:107], v[182:185], v[222:225], v[104:107]
	v_mfma_f32_16x16x32_bf16 v[72:75], v[202:205], v[222:225], v[72:75]
	v_mfma_f32_16x16x32_bf16 v[100:103], v[182:185], v[230:233], v[100:103]
	v_mfma_f32_16x16x32_bf16 v[68:71], v[202:205], v[230:233], v[68:71]
	v_mfma_f32_16x16x32_bf16 v[96:99], v[182:185], v[238:241], v[96:99]
	v_mfma_f32_16x16x32_bf16 v[64:67], v[202:205], v[238:241], v[64:67]
	v_mfma_f32_16x16x32_bf16 v[108:111], v[186:189], v[218:221], v[108:111]
	v_mfma_f32_16x16x32_bf16 v[76:79], v[206:209], v[218:221], v[76:79]
	v_mfma_f32_16x16x32_bf16 v[104:107], v[186:189], v[226:229], v[104:107]
	v_mfma_f32_16x16x32_bf16 v[72:75], v[206:209], v[226:229], v[72:75]
	v_mfma_f32_16x16x32_bf16 v[100:103], v[186:189], v[234:237], v[100:103]
	v_mfma_f32_16x16x32_bf16 v[68:71], v[206:209], v[234:237], v[68:71]
	v_mfma_f32_16x16x32_bf16 v[96:99], v[186:189], v[242:245], v[96:99]
	v_mfma_f32_16x16x32_bf16 v[64:67], v[206:209], v[242:245], v[64:67]
	s_barrier
	s_add_i32 s10, s16, s63
	s_mov_b32 m0, s10
	ds_read_b128 v[214:217], v199 offset:49152
	ds_read_b128 v[218:221], v199 offset:50176
	ds_read_b128 v[222:225], v199 offset:51200
	ds_read_b128 v[226:229], v199 offset:52224
	ds_read_b128 v[230:233], v199 offset:53248
	ds_read_b128 v[234:237], v199 offset:54272
	ds_read_b128 v[238:241], v199 offset:55296
	ds_read_b128 v[242:245], v199 offset:56320
	global_load_lds_dwordx4 v154, s[98:99]
	s_add_i32 m0, s10, 0x2000
	s_add_u32 s8, s8, 0x80080
	s_addc_u32 s9, s9, 0
	s_add_i32 s10, s17, s63
	global_load_lds_dwordx4 v158, s[98:99]
	s_mov_b32 m0, s10
	s_nop 0
	global_load_lds_dwordx4 v154, s[8:9]
	s_add_i32 m0, s10, 0x2000
	s_nop 0
	global_load_lds_dwordx4 v158, s[8:9]
	s_mov_b32 m0, s82
	s_nop 0
	global_load_lds_dwordx4 v152, s[100:101]
	s_mov_b32 m0, s83
	s_nop 0
	global_load_lds_dwordx4 v156, s[100:101]
	s_waitcnt vmcnt(8)
	s_waitcnt lgkmcnt(0)
	s_barrier
	v_mfma_f32_16x16x32_bf16 v[48:51], v[148:151], v[214:217], v[48:51]
	v_mfma_f32_16x16x32_bf16 v[16:19], v[174:177], v[214:217], v[16:19]
	v_mfma_f32_16x16x32_bf16 v[52:55], v[148:151], v[222:225], v[52:55]
	v_mfma_f32_16x16x32_bf16 v[24:27], v[174:177], v[222:225], v[24:27]
	v_mfma_f32_16x16x32_bf16 v[60:63], v[148:151], v[230:233], v[60:63]
	v_mfma_f32_16x16x32_bf16 v[28:31], v[174:177], v[230:233], v[28:31]
	v_mfma_f32_16x16x32_bf16 v[56:59], v[148:151], v[238:241], v[56:59]
	v_mfma_f32_16x16x32_bf16 v[20:23], v[174:177], v[238:241], v[20:23]
	v_mfma_f32_16x16x32_bf16 v[48:51], v[170:173], v[218:221], v[48:51]
	v_mfma_f32_16x16x32_bf16 v[16:19], v[178:181], v[218:221], v[16:19]
	v_mfma_f32_16x16x32_bf16 v[52:55], v[170:173], v[226:229], v[52:55]
	v_mfma_f32_16x16x32_bf16 v[24:27], v[178:181], v[226:229], v[24:27]
	v_mfma_f32_16x16x32_bf16 v[60:63], v[170:173], v[234:237], v[60:63]
	v_mfma_f32_16x16x32_bf16 v[28:31], v[178:181], v[234:237], v[28:31]
	v_mfma_f32_16x16x32_bf16 v[56:59], v[170:173], v[242:245], v[56:59]
	v_mfma_f32_16x16x32_bf16 v[20:23], v[178:181], v[242:245], v[20:23]
	v_mfma_f32_16x16x32_bf16 v[44:47], v[182:185], v[214:217], v[44:47]
	v_mfma_f32_16x16x32_bf16 v[12:15], v[202:205], v[214:217], v[12:15]
	v_mfma_f32_16x16x32_bf16 v[40:43], v[182:185], v[222:225], v[40:43]
	v_mfma_f32_16x16x32_bf16 v[8:11], v[202:205], v[222:225], v[8:11]
	v_mfma_f32_16x16x32_bf16 v[36:39], v[182:185], v[230:233], v[36:39]
	v_mfma_f32_16x16x32_bf16 v[4:7], v[202:205], v[230:233], v[4:7]
	v_mfma_f32_16x16x32_bf16 v[32:35], v[182:185], v[238:241], v[32:35]
	v_mfma_f32_16x16x32_bf16 v[0:3], v[202:205], v[238:241], v[0:3]
	v_mfma_f32_16x16x32_bf16 v[44:47], v[186:189], v[218:221], v[44:47]
	v_mfma_f32_16x16x32_bf16 v[12:15], v[206:209], v[218:221], v[12:15]
	v_mfma_f32_16x16x32_bf16 v[40:43], v[186:189], v[226:229], v[40:43]
	v_mfma_f32_16x16x32_bf16 v[8:11], v[206:209], v[226:229], v[8:11]
	v_mfma_f32_16x16x32_bf16 v[36:39], v[186:189], v[234:237], v[36:39]
	v_mfma_f32_16x16x32_bf16 v[4:7], v[206:209], v[234:237], v[4:7]
	v_mfma_f32_16x16x32_bf16 v[32:35], v[186:189], v[242:245], v[32:35]
	v_mfma_f32_16x16x32_bf16 v[0:3], v[206:209], v[242:245], v[0:3]
	s_barrier
	s_add_i32 s15, s15, 2
	s_add_u32 s6, s6, 0x100
	s_addc_u32 s7, s7, 0
	s_add_u32 s12, s12, 0x100
	s_addc_u32 s13, s13, 0
	s_cmp_gt_u32 s15, 29
.LBB0_636:
	ds_read_b128 v[148:151], v197
	ds_read_b128 v[170:173], v197 offset:1024
	ds_read_b128 v[174:177], v197 offset:2048
	ds_read_b128 v[178:181], v197 offset:3072
	ds_read_b128 v[182:185], v198
	ds_read_b128 v[186:189], v198 offset:1024
	ds_read_b128 v[202:205], v198 offset:2048
	ds_read_b128 v[206:209], v198 offset:3072
	s_add_u32 s8, s6, 0xfff80080
	s_addc_u32 s9, s7, -1
	s_cmp_eq_u32 s15, 28
	s_cselect_b32 s11, s69, s9
	s_cselect_b32 s10, s68, s8
	s_cselect_b32 s9, s1, s13
	s_cselect_b32 s8, s3, s12
	s_add_i32 m0, s72, 0xc000
	ds_read_b128 v[214:217], v199
	ds_read_b128 v[218:221], v199 offset:1024
	ds_read_b128 v[222:225], v199 offset:2048
	ds_read_b128 v[226:229], v199 offset:3072
	ds_read_b128 v[230:233], v199 offset:4096
	ds_read_b128 v[234:237], v199 offset:5120
	ds_read_b128 v[238:241], v199 offset:6144
	ds_read_b128 v[242:245], v199 offset:7168
	global_load_lds_dwordx4 v162, s[6:7]
	s_add_i32 m0, s72, 0xe000
	s_nop 0
	global_load_lds_dwordx4 v164, s[6:7]
	s_waitcnt vmcnt(8)
	s_waitcnt lgkmcnt(0)
	s_barrier
	v_mfma_f32_16x16x32_bf16 v[112:115], v[148:151], v[214:217], v[112:115]
	v_mfma_f32_16x16x32_bf16 v[80:83], v[174:177], v[214:217], v[80:83]
	v_mfma_f32_16x16x32_bf16 v[116:119], v[148:151], v[222:225], v[116:119]
	v_mfma_f32_16x16x32_bf16 v[88:91], v[174:177], v[222:225], v[88:91]
	v_mfma_f32_16x16x32_bf16 v[124:127], v[148:151], v[230:233], v[124:127]
	v_mfma_f32_16x16x32_bf16 v[92:95], v[174:177], v[230:233], v[92:95]
	v_mfma_f32_16x16x32_bf16 v[120:123], v[148:151], v[238:241], v[120:123]
	v_mfma_f32_16x16x32_bf16 v[84:87], v[174:177], v[238:241], v[84:87]
	v_mfma_f32_16x16x32_bf16 v[112:115], v[170:173], v[218:221], v[112:115]
	v_mfma_f32_16x16x32_bf16 v[80:83], v[178:181], v[218:221], v[80:83]
	v_mfma_f32_16x16x32_bf16 v[116:119], v[170:173], v[226:229], v[116:119]
	v_mfma_f32_16x16x32_bf16 v[88:91], v[178:181], v[226:229], v[88:91]
	v_mfma_f32_16x16x32_bf16 v[124:127], v[170:173], v[234:237], v[124:127]
	v_mfma_f32_16x16x32_bf16 v[92:95], v[178:181], v[234:237], v[92:95]
	v_mfma_f32_16x16x32_bf16 v[120:123], v[170:173], v[242:245], v[120:123]
	v_mfma_f32_16x16x32_bf16 v[84:87], v[178:181], v[242:245], v[84:87]
	v_mfma_f32_16x16x32_bf16 v[108:111], v[182:185], v[214:217], v[108:111]
	v_mfma_f32_16x16x32_bf16 v[76:79], v[202:205], v[214:217], v[76:79]
	v_mfma_f32_16x16x32_bf16 v[104:107], v[182:185], v[222:225], v[104:107]
	v_mfma_f32_16x16x32_bf16 v[72:75], v[202:205], v[222:225], v[72:75]
	v_mfma_f32_16x16x32_bf16 v[100:103], v[182:185], v[230:233], v[100:103]
	v_mfma_f32_16x16x32_bf16 v[68:71], v[202:205], v[230:233], v[68:71]
	v_mfma_f32_16x16x32_bf16 v[96:99], v[182:185], v[238:241], v[96:99]
	v_mfma_f32_16x16x32_bf16 v[64:67], v[202:205], v[238:241], v[64:67]
	v_mfma_f32_16x16x32_bf16 v[108:111], v[186:189], v[218:221], v[108:111]
	v_mfma_f32_16x16x32_bf16 v[76:79], v[206:209], v[218:221], v[76:79]
	v_mfma_f32_16x16x32_bf16 v[104:107], v[186:189], v[226:229], v[104:107]
	v_mfma_f32_16x16x32_bf16 v[72:75], v[206:209], v[226:229], v[72:75]
	v_mfma_f32_16x16x32_bf16 v[100:103], v[186:189], v[234:237], v[100:103]
	v_mfma_f32_16x16x32_bf16 v[68:71], v[206:209], v[234:237], v[68:71]
	v_mfma_f32_16x16x32_bf16 v[96:99], v[186:189], v[242:245], v[96:99]
	v_mfma_f32_16x16x32_bf16 v[64:67], v[206:209], v[242:245], v[64:67]
	s_barrier
	s_add_i32 s16, s94, s63
	s_add_u32 s98, s8, s40
	s_addc_u32 s99, s9, s41
	s_mov_b32 m0, s16
	ds_read_b128 v[214:217], v199 offset:16384
	ds_read_b128 v[218:221], v199 offset:17408
	ds_read_b128 v[222:225], v199 offset:18432
	ds_read_b128 v[226:229], v199 offset:19456
	ds_read_b128 v[230:233], v199 offset:20480
	ds_read_b128 v[234:237], v199 offset:21504
	ds_read_b128 v[238:241], v199 offset:22528
	ds_read_b128 v[242:245], v199 offset:23552
	global_load_lds_dwordx4 v154, s[8:9]
	s_add_i32 m0, s16, 0x2000
	s_add_u32 s16, s8, 0x80000
	s_addc_u32 s17, s9, 0
	s_add_i32 s18, s95, s63
	global_load_lds_dwordx4 v158, s[8:9]
	s_mov_b32 m0, s18
	s_add_u32 s100, s10, s40
	s_addc_u32 s101, s11, s41
	global_load_lds_dwordx4 v154, s[16:17]
	s_add_i32 m0, s18, 0x2000
	s_nop 0
	global_load_lds_dwordx4 v158, s[16:17]
	s_mov_b32 m0, s72
	s_nop 0
	global_load_lds_dwordx4 v152, s[10:11]
	s_mov_b32 m0, s73
	s_nop 0
	global_load_lds_dwordx4 v156, s[10:11]
	s_waitcnt vmcnt(8)
	s_waitcnt lgkmcnt(0)
	s_barrier
	v_mfma_f32_16x16x32_bf16 v[48:51], v[148:151], v[214:217], v[48:51]
	v_mfma_f32_16x16x32_bf16 v[16:19], v[174:177], v[214:217], v[16:19]
	v_mfma_f32_16x16x32_bf16 v[52:55], v[148:151], v[222:225], v[52:55]
	v_mfma_f32_16x16x32_bf16 v[24:27], v[174:177], v[222:225], v[24:27]
	v_mfma_f32_16x16x32_bf16 v[60:63], v[148:151], v[230:233], v[60:63]
	v_mfma_f32_16x16x32_bf16 v[28:31], v[174:177], v[230:233], v[28:31]
	v_mfma_f32_16x16x32_bf16 v[56:59], v[148:151], v[238:241], v[56:59]
	v_mfma_f32_16x16x32_bf16 v[20:23], v[174:177], v[238:241], v[20:23]
	v_mfma_f32_16x16x32_bf16 v[48:51], v[170:173], v[218:221], v[48:51]
	v_mfma_f32_16x16x32_bf16 v[16:19], v[178:181], v[218:221], v[16:19]
	v_mfma_f32_16x16x32_bf16 v[52:55], v[170:173], v[226:229], v[52:55]
	v_mfma_f32_16x16x32_bf16 v[24:27], v[178:181], v[226:229], v[24:27]
	v_mfma_f32_16x16x32_bf16 v[60:63], v[170:173], v[234:237], v[60:63]
	v_mfma_f32_16x16x32_bf16 v[28:31], v[178:181], v[234:237], v[28:31]
	v_mfma_f32_16x16x32_bf16 v[56:59], v[170:173], v[242:245], v[56:59]
	v_mfma_f32_16x16x32_bf16 v[20:23], v[178:181], v[242:245], v[20:23]
	v_mfma_f32_16x16x32_bf16 v[44:47], v[182:185], v[214:217], v[44:47]
	v_mfma_f32_16x16x32_bf16 v[12:15], v[202:205], v[214:217], v[12:15]
	v_mfma_f32_16x16x32_bf16 v[40:43], v[182:185], v[222:225], v[40:43]
	v_mfma_f32_16x16x32_bf16 v[8:11], v[202:205], v[222:225], v[8:11]
	v_mfma_f32_16x16x32_bf16 v[36:39], v[182:185], v[230:233], v[36:39]
	v_mfma_f32_16x16x32_bf16 v[4:7], v[202:205], v[230:233], v[4:7]
	v_mfma_f32_16x16x32_bf16 v[32:35], v[182:185], v[238:241], v[32:35]
	v_mfma_f32_16x16x32_bf16 v[0:3], v[202:205], v[238:241], v[0:3]
	v_mfma_f32_16x16x32_bf16 v[44:47], v[186:189], v[218:221], v[44:47]
	v_mfma_f32_16x16x32_bf16 v[12:15], v[206:209], v[218:221], v[12:15]
	v_mfma_f32_16x16x32_bf16 v[40:43], v[186:189], v[226:229], v[40:43]
	v_mfma_f32_16x16x32_bf16 v[8:11], v[206:209], v[226:229], v[8:11]
	v_mfma_f32_16x16x32_bf16 v[36:39], v[186:189], v[234:237], v[36:39]
	v_mfma_f32_16x16x32_bf16 v[4:7], v[206:209], v[234:237], v[4:7]
	v_mfma_f32_16x16x32_bf16 v[32:35], v[186:189], v[242:245], v[32:35]
	v_mfma_f32_16x16x32_bf16 v[0:3], v[206:209], v[242:245], v[0:3]
	s_barrier
	s_add_i32 s16, 0, 0x18000
	s_add_i32 s17, 0, 0x1c000
	v_add_u32_e32 v178, s16, v196
	v_add_u32_e32 v201, s17, v196
	ds_read_b128 v[148:151], v178
	ds_read_b128 v[170:173], v178 offset:1024
	ds_read_b128 v[174:177], v178 offset:2048
	ds_read_b128 v[178:181], v178 offset:3072
	ds_read_b128 v[182:185], v201
	ds_read_b128 v[186:189], v201 offset:1024
	ds_read_b128 v[202:205], v201 offset:2048
	ds_read_b128 v[206:209], v201 offset:3072
	s_add_u32 s10, s10, 0x80000
	s_addc_u32 s11, s11, 0
	s_mov_b32 m0, s74
	ds_read_b128 v[214:217], v199 offset:32768
	ds_read_b128 v[218:221], v199 offset:33792
	ds_read_b128 v[222:225], v199 offset:34816
	ds_read_b128 v[226:229], v199 offset:35840
	ds_read_b128 v[230:233], v199 offset:36864
	ds_read_b128 v[234:237], v199 offset:37888
	ds_read_b128 v[238:241], v199 offset:38912
	ds_read_b128 v[242:245], v199 offset:39936
	global_load_lds_dwordx4 v152, s[10:11]
	s_mov_b32 m0, s75
	s_nop 0
	global_load_lds_dwordx4 v156, s[10:11]
	s_waitcnt vmcnt(8)
	s_waitcnt lgkmcnt(0)
	s_barrier
	v_mfma_f32_16x16x32_bf16 v[112:115], v[148:151], v[214:217], v[112:115]
	v_mfma_f32_16x16x32_bf16 v[80:83], v[174:177], v[214:217], v[80:83]
	v_mfma_f32_16x16x32_bf16 v[116:119], v[148:151], v[222:225], v[116:119]
	v_mfma_f32_16x16x32_bf16 v[88:91], v[174:177], v[222:225], v[88:91]
	v_mfma_f32_16x16x32_bf16 v[124:127], v[148:151], v[230:233], v[124:127]
	v_mfma_f32_16x16x32_bf16 v[92:95], v[174:177], v[230:233], v[92:95]
	v_mfma_f32_16x16x32_bf16 v[120:123], v[148:151], v[238:241], v[120:123]
	v_mfma_f32_16x16x32_bf16 v[84:87], v[174:177], v[238:241], v[84:87]
	v_mfma_f32_16x16x32_bf16 v[112:115], v[170:173], v[218:221], v[112:115]
	v_mfma_f32_16x16x32_bf16 v[80:83], v[178:181], v[218:221], v[80:83]
	v_mfma_f32_16x16x32_bf16 v[116:119], v[170:173], v[226:229], v[116:119]
	v_mfma_f32_16x16x32_bf16 v[88:91], v[178:181], v[226:229], v[88:91]
	v_mfma_f32_16x16x32_bf16 v[124:127], v[170:173], v[234:237], v[124:127]
	v_mfma_f32_16x16x32_bf16 v[92:95], v[178:181], v[234:237], v[92:95]
	v_mfma_f32_16x16x32_bf16 v[120:123], v[170:173], v[242:245], v[120:123]
	v_mfma_f32_16x16x32_bf16 v[84:87], v[178:181], v[242:245], v[84:87]
	v_mfma_f32_16x16x32_bf16 v[108:111], v[182:185], v[214:217], v[108:111]
	v_mfma_f32_16x16x32_bf16 v[76:79], v[202:205], v[214:217], v[76:79]
	v_mfma_f32_16x16x32_bf16 v[104:107], v[182:185], v[222:225], v[104:107]
	v_mfma_f32_16x16x32_bf16 v[72:75], v[202:205], v[222:225], v[72:75]
	v_mfma_f32_16x16x32_bf16 v[100:103], v[182:185], v[230:233], v[100:103]
	v_mfma_f32_16x16x32_bf16 v[68:71], v[202:205], v[230:233], v[68:71]
	v_mfma_f32_16x16x32_bf16 v[96:99], v[182:185], v[238:241], v[96:99]
	v_mfma_f32_16x16x32_bf16 v[64:67], v[202:205], v[238:241], v[64:67]
	v_mfma_f32_16x16x32_bf16 v[108:111], v[186:189], v[218:221], v[108:111]
	v_mfma_f32_16x16x32_bf16 v[76:79], v[206:209], v[218:221], v[76:79]
	v_mfma_f32_16x16x32_bf16 v[104:107], v[186:189], v[226:229], v[104:107]
	v_mfma_f32_16x16x32_bf16 v[72:75], v[206:209], v[226:229], v[72:75]
	v_mfma_f32_16x16x32_bf16 v[100:103], v[186:189], v[234:237], v[100:103]
	v_mfma_f32_16x16x32_bf16 v[68:71], v[206:209], v[234:237], v[68:71]
	v_mfma_f32_16x16x32_bf16 v[96:99], v[186:189], v[242:245], v[96:99]
	v_mfma_f32_16x16x32_bf16 v[64:67], v[206:209], v[242:245], v[64:67]
	s_barrier
	s_add_i32 s10, s16, s63
	s_mov_b32 m0, s10
	ds_read_b128 v[214:217], v199 offset:49152
	ds_read_b128 v[218:221], v199 offset:50176
	ds_read_b128 v[222:225], v199 offset:51200
	ds_read_b128 v[226:229], v199 offset:52224
	ds_read_b128 v[230:233], v199 offset:53248
	ds_read_b128 v[234:237], v199 offset:54272
	ds_read_b128 v[238:241], v199 offset:55296
	ds_read_b128 v[242:245], v199 offset:56320
	global_load_lds_dwordx4 v154, s[98:99]
	s_add_i32 m0, s10, 0x2000
	s_add_u32 s8, s8, 0x80080
	s_addc_u32 s9, s9, 0
	s_add_i32 s10, s17, s63
	global_load_lds_dwordx4 v158, s[98:99]
	s_mov_b32 m0, s10
	s_nop 0
	global_load_lds_dwordx4 v154, s[8:9]
	s_add_i32 m0, s10, 0x2000
	s_nop 0
	global_load_lds_dwordx4 v158, s[8:9]
	s_mov_b32 m0, s82
	s_nop 0
	global_load_lds_dwordx4 v152, s[100:101]
	s_mov_b32 m0, s83
	s_nop 0
	global_load_lds_dwordx4 v156, s[100:101]
	s_waitcnt vmcnt(8)
	s_waitcnt lgkmcnt(0)
	s_barrier
	v_mfma_f32_16x16x32_bf16 v[48:51], v[148:151], v[214:217], v[48:51]
	v_mfma_f32_16x16x32_bf16 v[16:19], v[174:177], v[214:217], v[16:19]
	v_mfma_f32_16x16x32_bf16 v[52:55], v[148:151], v[222:225], v[52:55]
	v_mfma_f32_16x16x32_bf16 v[24:27], v[174:177], v[222:225], v[24:27]
	v_mfma_f32_16x16x32_bf16 v[60:63], v[148:151], v[230:233], v[60:63]
	v_mfma_f32_16x16x32_bf16 v[28:31], v[174:177], v[230:233], v[28:31]
	v_mfma_f32_16x16x32_bf16 v[56:59], v[148:151], v[238:241], v[56:59]
	v_mfma_f32_16x16x32_bf16 v[20:23], v[174:177], v[238:241], v[20:23]
	v_mfma_f32_16x16x32_bf16 v[48:51], v[170:173], v[218:221], v[48:51]
	v_mfma_f32_16x16x32_bf16 v[16:19], v[178:181], v[218:221], v[16:19]
	v_mfma_f32_16x16x32_bf16 v[52:55], v[170:173], v[226:229], v[52:55]
	v_mfma_f32_16x16x32_bf16 v[24:27], v[178:181], v[226:229], v[24:27]
	v_mfma_f32_16x16x32_bf16 v[60:63], v[170:173], v[234:237], v[60:63]
	v_mfma_f32_16x16x32_bf16 v[28:31], v[178:181], v[234:237], v[28:31]
	v_mfma_f32_16x16x32_bf16 v[56:59], v[170:173], v[242:245], v[56:59]
	v_mfma_f32_16x16x32_bf16 v[20:23], v[178:181], v[242:245], v[20:23]
	v_mfma_f32_16x16x32_bf16 v[44:47], v[182:185], v[214:217], v[44:47]
	v_mfma_f32_16x16x32_bf16 v[12:15], v[202:205], v[214:217], v[12:15]
	v_mfma_f32_16x16x32_bf16 v[40:43], v[182:185], v[222:225], v[40:43]
	v_mfma_f32_16x16x32_bf16 v[8:11], v[202:205], v[222:225], v[8:11]
	v_mfma_f32_16x16x32_bf16 v[36:39], v[182:185], v[230:233], v[36:39]
	v_mfma_f32_16x16x32_bf16 v[4:7], v[202:205], v[230:233], v[4:7]
	v_mfma_f32_16x16x32_bf16 v[32:35], v[182:185], v[238:241], v[32:35]
	v_mfma_f32_16x16x32_bf16 v[0:3], v[202:205], v[238:241], v[0:3]
	v_mfma_f32_16x16x32_bf16 v[44:47], v[186:189], v[218:221], v[44:47]
	v_mfma_f32_16x16x32_bf16 v[12:15], v[206:209], v[218:221], v[12:15]
	v_mfma_f32_16x16x32_bf16 v[40:43], v[186:189], v[226:229], v[40:43]
	v_mfma_f32_16x16x32_bf16 v[8:11], v[206:209], v[226:229], v[8:11]
	v_mfma_f32_16x16x32_bf16 v[36:39], v[186:189], v[234:237], v[36:39]
	v_mfma_f32_16x16x32_bf16 v[4:7], v[206:209], v[234:237], v[4:7]
	v_mfma_f32_16x16x32_bf16 v[32:35], v[186:189], v[242:245], v[32:35]
	v_mfma_f32_16x16x32_bf16 v[0:3], v[206:209], v[242:245], v[0:3]
	s_barrier
	s_add_i32 s15, s15, 2
	s_add_u32 s6, s6, 0x100
	s_addc_u32 s7, s7, 0
	s_add_u32 s12, s12, 0x100
	s_addc_u32 s13, s13, 0
	s_cmp_gt_u32 s15, 29
	s_cbranch_scc0 .LBB0_636
	s_setprio 0
	s_and_b64 vcc, exec, s[42:43]
	s_cbranch_vccz .LBB0_639
	s_barrier

.LBB0_875:
	s_mov_b32 s1, -2
	s_mov_b64 s[4:5], s[22:23]
	s_cmp_ge_u32 s97, 0x100
	s_cbranch_scc0 .Lkprio_3
	s_setprio 1
.Lkprio_3:
	ds_read_b128 v[128:131], v188
	ds_read_b128 v[132:135], v188 offset:1024
	ds_read_b128 v[136:139], v188 offset:2048
	ds_read_b128 v[140:143], v188 offset:3072
	ds_read_b128 v[144:147], v189
	ds_read_b128 v[148:151], v189 offset:1024
	ds_read_b128 v[166:169], v189 offset:2048
	ds_read_b128 v[170:173], v189 offset:3072
	s_add_u32 s40, s38, 0x100
	s_addc_u32 s41, s39, 0
	s_cmpk_eq_i32 s1, 0x52
	s_cselect_b32 s45, s37, s41
	s_cselect_b32 s44, s36, s40
	s_cselect_b32 s43, s17, s5
	s_cselect_b32 s42, s16, s4
	s_add_i32 m0, s48, 0xc000
	ds_read_b128 v[174:177], v190
	ds_read_b128 v[178:181], v190 offset:1024
	ds_read_b128 v[194:197], v190 offset:2048
	ds_read_b128 v[198:201], v190 offset:3072
	ds_read_b128 v[202:205], v190 offset:4096
	ds_read_b128 v[206:209], v190 offset:5120
	ds_read_b128 v[210:213], v190 offset:6144
	ds_read_b128 v[214:217], v190 offset:7168
	global_load_lds_dwordx4 v160, s[38:39]
	s_add_i32 m0, s48, 0xe000
	s_nop 0
	global_load_lds_dwordx4 v162, s[38:39]
	s_waitcnt vmcnt(8)
	s_waitcnt lgkmcnt(0)
	s_barrier
	v_mfma_f32_16x16x32_bf16 v[124:127], v[128:131], v[174:177], 0
	v_mfma_f32_16x16x32_bf16 v[120:123], v[136:139], v[174:177], 0
	v_mfma_f32_16x16x32_bf16 v[108:111], v[128:131], v[194:197], 0
	v_mfma_f32_16x16x32_bf16 v[104:107], v[136:139], v[194:197], 0
	v_mfma_f32_16x16x32_bf16 v[92:95], v[128:131], v[202:205], 0
	v_mfma_f32_16x16x32_bf16 v[88:91], v[136:139], v[202:205], 0
	v_mfma_f32_16x16x32_bf16 v[76:79], v[128:131], v[210:213], 0
	v_mfma_f32_16x16x32_bf16 v[72:75], v[136:139], v[210:213], 0
	v_mfma_f32_16x16x32_bf16 v[124:127], v[132:135], v[178:181], v[124:127]
	v_mfma_f32_16x16x32_bf16 v[120:123], v[140:143], v[178:181], v[120:123]
	v_mfma_f32_16x16x32_bf16 v[108:111], v[132:135], v[198:201], v[108:111]
	v_mfma_f32_16x16x32_bf16 v[104:107], v[140:143], v[198:201], v[104:107]
	v_mfma_f32_16x16x32_bf16 v[92:95], v[132:135], v[206:209], v[92:95]
	v_mfma_f32_16x16x32_bf16 v[88:91], v[140:143], v[206:209], v[88:91]
	v_mfma_f32_16x16x32_bf16 v[76:79], v[132:135], v[214:217], v[76:79]
	v_mfma_f32_16x16x32_bf16 v[72:75], v[140:143], v[214:217], v[72:75]
	v_mfma_f32_16x16x32_bf16 v[116:119], v[144:147], v[174:177], 0
	v_mfma_f32_16x16x32_bf16 v[112:115], v[166:169], v[174:177], 0
	v_mfma_f32_16x16x32_bf16 v[100:103], v[144:147], v[194:197], 0
	v_mfma_f32_16x16x32_bf16 v[96:99], v[166:169], v[194:197], 0
	v_mfma_f32_16x16x32_bf16 v[84:87], v[144:147], v[202:205], 0
	v_mfma_f32_16x16x32_bf16 v[80:83], v[166:169], v[202:205], 0
	v_mfma_f32_16x16x32_bf16 v[68:71], v[144:147], v[210:213], 0
	v_mfma_f32_16x16x32_bf16 v[64:67], v[166:169], v[210:213], 0
	v_mfma_f32_16x16x32_bf16 v[116:119], v[148:151], v[178:181], v[116:119]
	v_mfma_f32_16x16x32_bf16 v[112:115], v[170:173], v[178:181], v[112:115]
	v_mfma_f32_16x16x32_bf16 v[100:103], v[148:151], v[198:201], v[100:103]
	v_mfma_f32_16x16x32_bf16 v[96:99], v[170:173], v[198:201], v[96:99]
	v_mfma_f32_16x16x32_bf16 v[84:87], v[148:151], v[206:209], v[84:87]
	v_mfma_f32_16x16x32_bf16 v[80:83], v[170:173], v[206:209], v[80:83]
	v_mfma_f32_16x16x32_bf16 v[68:71], v[148:151], v[214:217], v[68:71]
	v_mfma_f32_16x16x32_bf16 v[64:67], v[170:173], v[214:217], v[64:67]
	s_barrier
	s_add_i32 s3, s70, s33
	s_add_u32 s98, s42, s24
	s_addc_u32 s99, s43, s25
	s_mov_b32 m0, s3
	ds_read_b128 v[174:177], v190 offset:16384
	ds_read_b128 v[178:181], v190 offset:17408
	ds_read_b128 v[194:197], v190 offset:18432
	ds_read_b128 v[198:201], v190 offset:19456
	ds_read_b128 v[202:205], v190 offset:20480
	ds_read_b128 v[206:209], v190 offset:21504
	ds_read_b128 v[210:213], v190 offset:22528
	ds_read_b128 v[214:217], v190 offset:23552
	global_load_lds_dwordx4 v154, s[42:43]
	s_add_i32 m0, s3, 0x2000
	s_add_u32 s38, s42, 0x158000
	s_addc_u32 s39, s43, 0
	s_add_i32 s3, s71, s33
	global_load_lds_dwordx4 v158, s[42:43]
	s_mov_b32 m0, s3
	s_add_u32 s100, s44, s24
	s_addc_u32 s101, s45, s25
	global_load_lds_dwordx4 v154, s[38:39]
	s_add_i32 m0, s3, 0x2000
	s_nop 0
	global_load_lds_dwordx4 v158, s[38:39]
	s_mov_b32 m0, s48
	s_nop 0
	global_load_lds_dwordx4 v152, s[44:45]
	s_mov_b32 m0, s49
	s_nop 0
	global_load_lds_dwordx4 v156, s[44:45]
	s_waitcnt vmcnt(8)
	s_waitcnt lgkmcnt(0)
	s_barrier
	v_mfma_f32_16x16x32_bf16 v[60:63], v[128:131], v[174:177], 0
	v_mfma_f32_16x16x32_bf16 v[56:59], v[136:139], v[174:177], 0
	v_mfma_f32_16x16x32_bf16 v[44:47], v[128:131], v[194:197], 0
	v_mfma_f32_16x16x32_bf16 v[40:43], v[136:139], v[194:197], 0
	v_mfma_f32_16x16x32_bf16 v[28:31], v[128:131], v[202:205], 0
	v_mfma_f32_16x16x32_bf16 v[24:27], v[136:139], v[202:205], 0
	v_mfma_f32_16x16x32_bf16 v[12:15], v[128:131], v[210:213], 0
	v_mfma_f32_16x16x32_bf16 v[8:11], v[136:139], v[210:213], 0
	v_mfma_f32_16x16x32_bf16 v[60:63], v[132:135], v[178:181], v[60:63]
	v_mfma_f32_16x16x32_bf16 v[56:59], v[140:143], v[178:181], v[56:59]
	v_mfma_f32_16x16x32_bf16 v[44:47], v[132:135], v[198:201], v[44:47]
	v_mfma_f32_16x16x32_bf16 v[40:43], v[140:143], v[198:201], v[40:43]
	v_mfma_f32_16x16x32_bf16 v[28:31], v[132:135], v[206:209], v[28:31]
	v_mfma_f32_16x16x32_bf16 v[24:27], v[140:143], v[206:209], v[24:27]
	v_mfma_f32_16x16x32_bf16 v[12:15], v[132:135], v[214:217], v[12:15]
	v_mfma_f32_16x16x32_bf16 v[8:11], v[140:143], v[214:217], v[8:11]
	v_mfma_f32_16x16x32_bf16 v[52:55], v[144:147], v[174:177], 0
	v_mfma_f32_16x16x32_bf16 v[48:51], v[166:169], v[174:177], 0
	v_mfma_f32_16x16x32_bf16 v[36:39], v[144:147], v[194:197], 0
	v_mfma_f32_16x16x32_bf16 v[32:35], v[166:169], v[194:197], 0
	v_mfma_f32_16x16x32_bf16 v[20:23], v[144:147], v[202:205], 0
	v_mfma_f32_16x16x32_bf16 v[16:19], v[166:169], v[202:205], 0
	v_mfma_f32_16x16x32_bf16 v[4:7], v[144:147], v[210:213], 0
	v_mfma_f32_16x16x32_bf16 v[0:3], v[166:169], v[210:213], 0
	v_mfma_f32_16x16x32_bf16 v[52:55], v[148:151], v[178:181], v[52:55]
	v_mfma_f32_16x16x32_bf16 v[48:51], v[170:173], v[178:181], v[48:51]
	v_mfma_f32_16x16x32_bf16 v[36:39], v[148:151], v[198:201], v[36:39]
	v_mfma_f32_16x16x32_bf16 v[32:35], v[170:173], v[198:201], v[32:35]
	v_mfma_f32_16x16x32_bf16 v[20:23], v[148:151], v[206:209], v[20:23]
	v_mfma_f32_16x16x32_bf16 v[16:19], v[170:173], v[206:209], v[16:19]
	v_mfma_f32_16x16x32_bf16 v[4:7], v[148:151], v[214:217], v[4:7]
	v_mfma_f32_16x16x32_bf16 v[0:3], v[170:173], v[214:217], v[0:3]
	s_barrier
	s_add_i32 s3, 0, 0x18000
	s_add_i32 s73, 0, 0x1c000
	v_add_u32_e32 v140, s3, v187
	v_add_u32_e32 v170, s73, v187
	ds_read_b128 v[128:131], v140
	ds_read_b128 v[132:135], v140 offset:1024
	ds_read_b128 v[136:139], v140 offset:2048
	ds_read_b128 v[140:143], v140 offset:3072
	ds_read_b128 v[144:147], v170
	ds_read_b128 v[148:151], v170 offset:1024
	ds_read_b128 v[166:169], v170 offset:2048
	ds_read_b128 v[170:173], v170 offset:3072
	s_add_u32 s38, s44, 0x158000
	s_addc_u32 s39, s45, 0
	s_mov_b32 m0, s51
	ds_read_b128 v[174:177], v190 offset:32768
	ds_read_b128 v[178:181], v190 offset:33792
	ds_read_b128 v[194:197], v190 offset:34816
	ds_read_b128 v[198:201], v190 offset:35840
	ds_read_b128 v[202:205], v190 offset:36864
	ds_read_b128 v[206:209], v190 offset:37888
	ds_read_b128 v[210:213], v190 offset:38912
	ds_read_b128 v[214:217], v190 offset:39936
	global_load_lds_dwordx4 v152, s[38:39]
	s_mov_b32 m0, s52
	s_nop 0
	global_load_lds_dwordx4 v156, s[38:39]
	s_waitcnt vmcnt(8)
	s_waitcnt lgkmcnt(0)
	s_barrier
	v_mfma_f32_16x16x32_bf16 v[124:127], v[128:131], v[174:177], v[124:127]
	v_mfma_f32_16x16x32_bf16 v[120:123], v[136:139], v[174:177], v[120:123]
	v_mfma_f32_16x16x32_bf16 v[108:111], v[128:131], v[194:197], v[108:111]
	v_mfma_f32_16x16x32_bf16 v[104:107], v[136:139], v[194:197], v[104:107]
	v_mfma_f32_16x16x32_bf16 v[92:95], v[128:131], v[202:205], v[92:95]
	v_mfma_f32_16x16x32_bf16 v[88:91], v[136:139], v[202:205], v[88:91]
	v_mfma_f32_16x16x32_bf16 v[76:79], v[128:131], v[210:213], v[76:79]
	v_mfma_f32_16x16x32_bf16 v[72:75], v[136:139], v[210:213], v[72:75]
	v_mfma_f32_16x16x32_bf16 v[124:127], v[132:135], v[178:181], v[124:127]
	v_mfma_f32_16x16x32_bf16 v[120:123], v[140:143], v[178:181], v[120:123]
	v_mfma_f32_16x16x32_bf16 v[108:111], v[132:135], v[198:201], v[108:111]
	v_mfma_f32_16x16x32_bf16 v[104:107], v[140:143], v[198:201], v[104:107]
	v_mfma_f32_16x16x32_bf16 v[92:95], v[132:135], v[206:209], v[92:95]
	v_mfma_f32_16x16x32_bf16 v[88:91], v[140:143], v[206:209], v[88:91]
	v_mfma_f32_16x16x32_bf16 v[76:79], v[132:135], v[214:217], v[76:79]
	v_mfma_f32_16x16x32_bf16 v[72:75], v[140:143], v[214:217], v[72:75]
	v_mfma_f32_16x16x32_bf16 v[116:119], v[144:147], v[174:177], v[116:119]
	v_mfma_f32_16x16x32_bf16 v[112:115], v[166:169], v[174:177], v[112:115]
	v_mfma_f32_16x16x32_bf16 v[100:103], v[144:147], v[194:197], v[100:103]
	v_mfma_f32_16x16x32_bf16 v[96:99], v[166:169], v[194:197], v[96:99]
	v_mfma_f32_16x16x32_bf16 v[84:87], v[144:147], v[202:205], v[84:87]
	v_mfma_f32_16x16x32_bf16 v[80:83], v[166:169], v[202:205], v[80:83]
	v_mfma_f32_16x16x32_bf16 v[68:71], v[144:147], v[210:213], v[68:71]
	v_mfma_f32_16x16x32_bf16 v[64:67], v[166:169], v[210:213], v[64:67]
	v_mfma_f32_16x16x32_bf16 v[116:119], v[148:151], v[178:181], v[116:119]
	v_mfma_f32_16x16x32_bf16 v[112:115], v[170:173], v[178:181], v[112:115]
	v_mfma_f32_16x16x32_bf16 v[100:103], v[148:151], v[198:201], v[100:103]
	v_mfma_f32_16x16x32_bf16 v[96:99], v[170:173], v[198:201], v[96:99]
	v_mfma_f32_16x16x32_bf16 v[84:87], v[148:151], v[206:209], v[84:87]
	v_mfma_f32_16x16x32_bf16 v[80:83], v[170:173], v[206:209], v[80:83]
	v_mfma_f32_16x16x32_bf16 v[68:71], v[148:151], v[214:217], v[68:71]
	v_mfma_f32_16x16x32_bf16 v[64:67], v[170:173], v[214:217], v[64:67]
	s_barrier
	s_add_i32 s3, s3, s33
	s_mov_b32 m0, s3
	ds_read_b128 v[174:177], v190 offset:49152
	ds_read_b128 v[178:181], v190 offset:50176
	ds_read_b128 v[194:197], v190 offset:51200
	ds_read_b128 v[198:201], v190 offset:52224
	ds_read_b128 v[202:205], v190 offset:53248
	ds_read_b128 v[206:209], v190 offset:54272
	ds_read_b128 v[210:213], v190 offset:55296
	ds_read_b128 v[214:217], v190 offset:56320
	global_load_lds_dwordx4 v154, s[98:99]
	s_add_i32 m0, s3, 0x2000
	s_add_u32 s38, s42, 0x158080
	s_addc_u32 s39, s43, 0
	s_add_i32 s3, s73, s33
	global_load_lds_dwordx4 v158, s[98:99]
	s_mov_b32 m0, s3
	s_nop 0
	global_load_lds_dwordx4 v154, s[38:39]
	s_add_i32 m0, s3, 0x2000
	s_nop 0
	global_load_lds_dwordx4 v158, s[38:39]
	s_mov_b32 m0, s56
	s_nop 0
	global_load_lds_dwordx4 v152, s[100:101]
	s_mov_b32 m0, s57
	s_nop 0
	global_load_lds_dwordx4 v156, s[100:101]
	s_waitcnt vmcnt(8)
	s_waitcnt lgkmcnt(0)
	s_barrier
	v_mfma_f32_16x16x32_bf16 v[60:63], v[128:131], v[174:177], v[60:63]
	v_mfma_f32_16x16x32_bf16 v[56:59], v[136:139], v[174:177], v[56:59]
	v_mfma_f32_16x16x32_bf16 v[44:47], v[128:131], v[194:197], v[44:47]
	v_mfma_f32_16x16x32_bf16 v[40:43], v[136:139], v[194:197], v[40:43]
	v_mfma_f32_16x16x32_bf16 v[28:31], v[128:131], v[202:205], v[28:31]
	v_mfma_f32_16x16x32_bf16 v[24:27], v[136:139], v[202:205], v[24:27]
	v_mfma_f32_16x16x32_bf16 v[12:15], v[128:131], v[210:213], v[12:15]
	v_mfma_f32_16x16x32_bf16 v[8:11], v[136:139], v[210:213], v[8:11]
	v_mfma_f32_16x16x32_bf16 v[60:63], v[132:135], v[178:181], v[60:63]
	v_mfma_f32_16x16x32_bf16 v[56:59], v[140:143], v[178:181], v[56:59]
	v_mfma_f32_16x16x32_bf16 v[44:47], v[132:135], v[198:201], v[44:47]
	v_mfma_f32_16x16x32_bf16 v[40:43], v[140:143], v[198:201], v[40:43]
	v_mfma_f32_16x16x32_bf16 v[28:31], v[132:135], v[206:209], v[28:31]
	v_mfma_f32_16x16x32_bf16 v[24:27], v[140:143], v[206:209], v[24:27]
	v_mfma_f32_16x16x32_bf16 v[12:15], v[132:135], v[214:217], v[12:15]
	v_mfma_f32_16x16x32_bf16 v[8:11], v[140:143], v[214:217], v[8:11]
	v_mfma_f32_16x16x32_bf16 v[52:55], v[144:147], v[174:177], v[52:55]
	v_mfma_f32_16x16x32_bf16 v[48:51], v[166:169], v[174:177], v[48:51]
	v_mfma_f32_16x16x32_bf16 v[36:39], v[144:147], v[194:197], v[36:39]
	v_mfma_f32_16x16x32_bf16 v[32:35], v[166:169], v[194:197], v[32:35]
	v_mfma_f32_16x16x32_bf16 v[20:23], v[144:147], v[202:205], v[20:23]
	v_mfma_f32_16x16x32_bf16 v[16:19], v[166:169], v[202:205], v[16:19]
	v_mfma_f32_16x16x32_bf16 v[4:7], v[144:147], v[210:213], v[4:7]
	v_mfma_f32_16x16x32_bf16 v[0:3], v[166:169], v[210:213], v[0:3]
	v_mfma_f32_16x16x32_bf16 v[52:55], v[148:151], v[178:181], v[52:55]
	v_mfma_f32_16x16x32_bf16 v[48:51], v[170:173], v[178:181], v[48:51]
	v_mfma_f32_16x16x32_bf16 v[36:39], v[148:151], v[198:201], v[36:39]
	v_mfma_f32_16x16x32_bf16 v[32:35], v[170:173], v[198:201], v[32:35]
	v_mfma_f32_16x16x32_bf16 v[20:23], v[148:151], v[206:209], v[20:23]
	v_mfma_f32_16x16x32_bf16 v[16:19], v[170:173], v[206:209], v[16:19]
	v_mfma_f32_16x16x32_bf16 v[4:7], v[148:151], v[214:217], v[4:7]
	v_mfma_f32_16x16x32_bf16 v[0:3], v[170:173], v[214:217], v[0:3]
	s_barrier
	s_add_i32 s1, s1, 2
	s_add_u32 s4, s4, 0x100
	s_addc_u32 s5, s5, 0
	s_cmpk_gt_u32 s1, 0x53
	s_mov_b64 s[38:39], s[40:41]
.LBB0_876:
	ds_read_b128 v[128:131], v188
	ds_read_b128 v[132:135], v188 offset:1024
	ds_read_b128 v[136:139], v188 offset:2048
	ds_read_b128 v[140:143], v188 offset:3072
	ds_read_b128 v[144:147], v189
	ds_read_b128 v[148:151], v189 offset:1024
	ds_read_b128 v[166:169], v189 offset:2048
	ds_read_b128 v[170:173], v189 offset:3072
	s_add_u32 s40, s38, 0x100
	s_addc_u32 s41, s39, 0
	s_cmpk_eq_i32 s1, 0x52
	s_cselect_b32 s45, s37, s41
	s_cselect_b32 s44, s36, s40
	s_cselect_b32 s43, s17, s5
	s_cselect_b32 s42, s16, s4
	s_add_i32 m0, s48, 0xc000
	ds_read_b128 v[174:177], v190
	ds_read_b128 v[178:181], v190 offset:1024
	ds_read_b128 v[194:197], v190 offset:2048
	ds_read_b128 v[198:201], v190 offset:3072
	ds_read_b128 v[202:205], v190 offset:4096
	ds_read_b128 v[206:209], v190 offset:5120
	ds_read_b128 v[210:213], v190 offset:6144
	ds_read_b128 v[214:217], v190 offset:7168
	global_load_lds_dwordx4 v160, s[38:39]
	s_add_i32 m0, s48, 0xe000
	s_nop 0
	global_load_lds_dwordx4 v162, s[38:39]
	s_waitcnt vmcnt(8)
	s_waitcnt lgkmcnt(0)
	s_barrier
	v_mfma_f32_16x16x32_bf16 v[124:127], v[128:131], v[174:177], v[124:127]
	v_mfma_f32_16x16x32_bf16 v[120:123], v[136:139], v[174:177], v[120:123]
	v_mfma_f32_16x16x32_bf16 v[108:111], v[128:131], v[194:197], v[108:111]
	v_mfma_f32_16x16x32_bf16 v[104:107], v[136:139], v[194:197], v[104:107]
	v_mfma_f32_16x16x32_bf16 v[92:95], v[128:131], v[202:205], v[92:95]
	v_mfma_f32_16x16x32_bf16 v[88:91], v[136:139], v[202:205], v[88:91]
	v_mfma_f32_16x16x32_bf16 v[76:79], v[128:131], v[210:213], v[76:79]
	v_mfma_f32_16x16x32_bf16 v[72:75], v[136:139], v[210:213], v[72:75]
	v_mfma_f32_16x16x32_bf16 v[124:127], v[132:135], v[178:181], v[124:127]
	v_mfma_f32_16x16x32_bf16 v[120:123], v[140:143], v[178:181], v[120:123]
	v_mfma_f32_16x16x32_bf16 v[108:111], v[132:135], v[198:201], v[108:111]
	v_mfma_f32_16x16x32_bf16 v[104:107], v[140:143], v[198:201], v[104:107]
	v_mfma_f32_16x16x32_bf16 v[92:95], v[132:135], v[206:209], v[92:95]
	v_mfma_f32_16x16x32_bf16 v[88:91], v[140:143], v[206:209], v[88:91]
	v_mfma_f32_16x16x32_bf16 v[76:79], v[132:135], v[214:217], v[76:79]
	v_mfma_f32_16x16x32_bf16 v[72:75], v[140:143], v[214:217], v[72:75]
	v_mfma_f32_16x16x32_bf16 v[116:119], v[144:147], v[174:177], v[116:119]
	v_mfma_f32_16x16x32_bf16 v[112:115], v[166:169], v[174:177], v[112:115]
	v_mfma_f32_16x16x32_bf16 v[100:103], v[144:147], v[194:197], v[100:103]
	v_mfma_f32_16x16x32_bf16 v[96:99], v[166:169], v[194:197], v[96:99]
	v_mfma_f32_16x16x32_bf16 v[84:87], v[144:147], v[202:205], v[84:87]
	v_mfma_f32_16x16x32_bf16 v[80:83], v[166:169], v[202:205], v[80:83]
	v_mfma_f32_16x16x32_bf16 v[68:71], v[144:147], v[210:213], v[68:71]
	v_mfma_f32_16x16x32_bf16 v[64:67], v[166:169], v[210:213], v[64:67]
	v_mfma_f32_16x16x32_bf16 v[116:119], v[148:151], v[178:181], v[116:119]
	v_mfma_f32_16x16x32_bf16 v[112:115], v[170:173], v[178:181], v[112:115]
	v_mfma_f32_16x16x32_bf16 v[100:103], v[148:151], v[198:201], v[100:103]
	v_mfma_f32_16x16x32_bf16 v[96:99], v[170:173], v[198:201], v[96:99]
	v_mfma_f32_16x16x32_bf16 v[84:87], v[148:151], v[206:209], v[84:87]
	v_mfma_f32_16x16x32_bf16 v[80:83], v[170:173], v[206:209], v[80:83]
	v_mfma_f32_16x16x32_bf16 v[68:71], v[148:151], v[214:217], v[68:71]
	v_mfma_f32_16x16x32_bf16 v[64:67], v[170:173], v[214:217], v[64:67]
	s_barrier
	s_add_i32 s3, s70, s33
	s_add_u32 s98, s42, s24
	s_addc_u32 s99, s43, s25
	s_mov_b32 m0, s3
	ds_read_b128 v[174:177], v190 offset:16384
	ds_read_b128 v[178:181], v190 offset:17408
	ds_read_b128 v[194:197], v190 offset:18432
	ds_read_b128 v[198:201], v190 offset:19456
	ds_read_b128 v[202:205], v190 offset:20480
	ds_read_b128 v[206:209], v190 offset:21504
	ds_read_b128 v[210:213], v190 offset:22528
	ds_read_b128 v[214:217], v190 offset:23552
	global_load_lds_dwordx4 v154, s[42:43]
	s_add_i32 m0, s3, 0x2000
	s_add_u32 s38, s42, 0x158000
	s_addc_u32 s39, s43, 0
	s_add_i32 s3, s71, s33
	global_load_lds_dwordx4 v158, s[42:43]
	s_mov_b32 m0, s3
	s_add_u32 s100, s44, s24
	s_addc_u32 s101, s45, s25
	global_load_lds_dwordx4 v154, s[38:39]
	s_add_i32 m0, s3, 0x2000
	s_nop 0
	global_load_lds_dwordx4 v158, s[38:39]
	s_mov_b32 m0, s48
	s_nop 0
	global_load_lds_dwordx4 v152, s[44:45]
	s_mov_b32 m0, s49
	s_nop 0
	global_load_lds_dwordx4 v156, s[44:45]
	s_waitcnt vmcnt(8)
	s_waitcnt lgkmcnt(0)
	s_barrier
	v_mfma_f32_16x16x32_bf16 v[60:63], v[128:131], v[174:177], v[60:63]
	v_mfma_f32_16x16x32_bf16 v[56:59], v[136:139], v[174:177], v[56:59]
	v_mfma_f32_16x16x32_bf16 v[44:47], v[128:131], v[194:197], v[44:47]
	v_mfma_f32_16x16x32_bf16 v[40:43], v[136:139], v[194:197], v[40:43]
	v_mfma_f32_16x16x32_bf16 v[28:31], v[128:131], v[202:205], v[28:31]
	v_mfma_f32_16x16x32_bf16 v[24:27], v[136:139], v[202:205], v[24:27]
	v_mfma_f32_16x16x32_bf16 v[12:15], v[128:131], v[210:213], v[12:15]
	v_mfma_f32_16x16x32_bf16 v[8:11], v[136:139], v[210:213], v[8:11]
	v_mfma_f32_16x16x32_bf16 v[60:63], v[132:135], v[178:181], v[60:63]
	v_mfma_f32_16x16x32_bf16 v[56:59], v[140:143], v[178:181], v[56:59]
	v_mfma_f32_16x16x32_bf16 v[44:47], v[132:135], v[198:201], v[44:47]
	v_mfma_f32_16x16x32_bf16 v[40:43], v[140:143], v[198:201], v[40:43]
	v_mfma_f32_16x16x32_bf16 v[28:31], v[132:135], v[206:209], v[28:31]
	v_mfma_f32_16x16x32_bf16 v[24:27], v[140:143], v[206:209], v[24:27]
	v_mfma_f32_16x16x32_bf16 v[12:15], v[132:135], v[214:217], v[12:15]
	v_mfma_f32_16x16x32_bf16 v[8:11], v[140:143], v[214:217], v[8:11]
	v_mfma_f32_16x16x32_bf16 v[52:55], v[144:147], v[174:177], v[52:55]
	v_mfma_f32_16x16x32_bf16 v[48:51], v[166:169], v[174:177], v[48:51]
	v_mfma_f32_16x16x32_bf16 v[36:39], v[144:147], v[194:197], v[36:39]
	v_mfma_f32_16x16x32_bf16 v[32:35], v[166:169], v[194:197], v[32:35]
	v_mfma_f32_16x16x32_bf16 v[20:23], v[144:147], v[202:205], v[20:23]
	v_mfma_f32_16x16x32_bf16 v[16:19], v[166:169], v[202:205], v[16:19]
	v_mfma_f32_16x16x32_bf16 v[4:7], v[144:147], v[210:213], v[4:7]
	v_mfma_f32_16x16x32_bf16 v[0:3], v[166:169], v[210:213], v[0:3]
	v_mfma_f32_16x16x32_bf16 v[52:55], v[148:151], v[178:181], v[52:55]
	v_mfma_f32_16x16x32_bf16 v[48:51], v[170:173], v[178:181], v[48:51]
	v_mfma_f32_16x16x32_bf16 v[36:39], v[148:151], v[198:201], v[36:39]
	v_mfma_f32_16x16x32_bf16 v[32:35], v[170:173], v[198:201], v[32:35]
	v_mfma_f32_16x16x32_bf16 v[20:23], v[148:151], v[206:209], v[20:23]
	v_mfma_f32_16x16x32_bf16 v[16:19], v[170:173], v[206:209], v[16:19]
	v_mfma_f32_16x16x32_bf16 v[4:7], v[148:151], v[214:217], v[4:7]
	v_mfma_f32_16x16x32_bf16 v[0:3], v[170:173], v[214:217], v[0:3]
	s_barrier
	s_add_i32 s3, 0, 0x18000
	s_add_i32 s73, 0, 0x1c000
	v_add_u32_e32 v140, s3, v187
	v_add_u32_e32 v170, s73, v187
	ds_read_b128 v[128:131], v140
	ds_read_b128 v[132:135], v140 offset:1024
	ds_read_b128 v[136:139], v140 offset:2048
	ds_read_b128 v[140:143], v140 offset:3072
	ds_read_b128 v[144:147], v170
	ds_read_b128 v[148:151], v170 offset:1024
	ds_read_b128 v[166:169], v170 offset:2048
	ds_read_b128 v[170:173], v170 offset:3072
	s_add_u32 s38, s44, 0x158000
	s_addc_u32 s39, s45, 0
	s_mov_b32 m0, s51
	ds_read_b128 v[174:177], v190 offset:32768
	ds_read_b128 v[178:181], v190 offset:33792
	ds_read_b128 v[194:197], v190 offset:34816
	ds_read_b128 v[198:201], v190 offset:35840
	ds_read_b128 v[202:205], v190 offset:36864
	ds_read_b128 v[206:209], v190 offset:37888
	ds_read_b128 v[210:213], v190 offset:38912
	ds_read_b128 v[214:217], v190 offset:39936
	global_load_lds_dwordx4 v152, s[38:39]
	s_mov_b32 m0, s52
	s_nop 0
	global_load_lds_dwordx4 v156, s[38:39]
	s_waitcnt vmcnt(8)
	s_waitcnt lgkmcnt(0)
	s_barrier
	v_mfma_f32_16x16x32_bf16 v[124:127], v[128:131], v[174:177], v[124:127]
	v_mfma_f32_16x16x32_bf16 v[120:123], v[136:139], v[174:177], v[120:123]
	v_mfma_f32_16x16x32_bf16 v[108:111], v[128:131], v[194:197], v[108:111]
	v_mfma_f32_16x16x32_bf16 v[104:107], v[136:139], v[194:197], v[104:107]
	v_mfma_f32_16x16x32_bf16 v[92:95], v[128:131], v[202:205], v[92:95]
	v_mfma_f32_16x16x32_bf16 v[88:91], v[136:139], v[202:205], v[88:91]
	v_mfma_f32_16x16x32_bf16 v[76:79], v[128:131], v[210:213], v[76:79]
	v_mfma_f32_16x16x32_bf16 v[72:75], v[136:139], v[210:213], v[72:75]
	v_mfma_f32_16x16x32_bf16 v[124:127], v[132:135], v[178:181], v[124:127]
	v_mfma_f32_16x16x32_bf16 v[120:123], v[140:143], v[178:181], v[120:123]
	v_mfma_f32_16x16x32_bf16 v[108:111], v[132:135], v[198:201], v[108:111]
	v_mfma_f32_16x16x32_bf16 v[104:107], v[140:143], v[198:201], v[104:107]
	v_mfma_f32_16x16x32_bf16 v[92:95], v[132:135], v[206:209], v[92:95]
	v_mfma_f32_16x16x32_bf16 v[88:91], v[140:143], v[206:209], v[88:91]
	v_mfma_f32_16x16x32_bf16 v[76:79], v[132:135], v[214:217], v[76:79]
	v_mfma_f32_16x16x32_bf16 v[72:75], v[140:143], v[214:217], v[72:75]
	v_mfma_f32_16x16x32_bf16 v[116:119], v[144:147], v[174:177], v[116:119]
	v_mfma_f32_16x16x32_bf16 v[112:115], v[166:169], v[174:177], v[112:115]
	v_mfma_f32_16x16x32_bf16 v[100:103], v[144:147], v[194:197], v[100:103]
	v_mfma_f32_16x16x32_bf16 v[96:99], v[166:169], v[194:197], v[96:99]
	v_mfma_f32_16x16x32_bf16 v[84:87], v[144:147], v[202:205], v[84:87]
	v_mfma_f32_16x16x32_bf16 v[80:83], v[166:169], v[202:205], v[80:83]
	v_mfma_f32_16x16x32_bf16 v[68:71], v[144:147], v[210:213], v[68:71]
	v_mfma_f32_16x16x32_bf16 v[64:67], v[166:169], v[210:213], v[64:67]
	v_mfma_f32_16x16x32_bf16 v[116:119], v[148:151], v[178:181], v[116:119]
	v_mfma_f32_16x16x32_bf16 v[112:115], v[170:173], v[178:181], v[112:115]
	v_mfma_f32_16x16x32_bf16 v[100:103], v[148:151], v[198:201], v[100:103]
	v_mfma_f32_16x16x32_bf16 v[96:99], v[170:173], v[198:201], v[96:99]
	v_mfma_f32_16x16x32_bf16 v[84:87], v[148:151], v[206:209], v[84:87]
	v_mfma_f32_16x16x32_bf16 v[80:83], v[170:173], v[206:209], v[80:83]
	v_mfma_f32_16x16x32_bf16 v[68:71], v[148:151], v[214:217], v[68:71]
	v_mfma_f32_16x16x32_bf16 v[64:67], v[170:173], v[214:217], v[64:67]
	s_barrier
	s_add_i32 s3, s3, s33
	s_mov_b32 m0, s3
	ds_read_b128 v[174:177], v190 offset:49152
	ds_read_b128 v[178:181], v190 offset:50176
	ds_read_b128 v[194:197], v190 offset:51200
	ds_read_b128 v[198:201], v190 offset:52224
	ds_read_b128 v[202:205], v190 offset:53248
	ds_read_b128 v[206:209], v190 offset:54272
	ds_read_b128 v[210:213], v190 offset:55296
	ds_read_b128 v[214:217], v190 offset:56320
	global_load_lds_dwordx4 v154, s[98:99]
	s_add_i32 m0, s3, 0x2000
	s_add_u32 s38, s42, 0x158080
	s_addc_u32 s39, s43, 0
	s_add_i32 s3, s73, s33
	global_load_lds_dwordx4 v158, s[98:99]
	s_mov_b32 m0, s3
	s_nop 0
	global_load_lds_dwordx4 v154, s[38:39]
	s_add_i32 m0, s3, 0x2000
	s_nop 0
	global_load_lds_dwordx4 v158, s[38:39]
	s_mov_b32 m0, s56
	s_nop 0
	global_load_lds_dwordx4 v152, s[100:101]
	s_mov_b32 m0, s57
	s_nop 0
	global_load_lds_dwordx4 v156, s[100:101]
	s_waitcnt vmcnt(8)
	s_waitcnt lgkmcnt(0)
	s_barrier
	v_mfma_f32_16x16x32_bf16 v[60:63], v[128:131], v[174:177], v[60:63]
	v_mfma_f32_16x16x32_bf16 v[56:59], v[136:139], v[174:177], v[56:59]
	v_mfma_f32_16x16x32_bf16 v[44:47], v[128:131], v[194:197], v[44:47]
	v_mfma_f32_16x16x32_bf16 v[40:43], v[136:139], v[194:197], v[40:43]
	v_mfma_f32_16x16x32_bf16 v[28:31], v[128:131], v[202:205], v[28:31]
	v_mfma_f32_16x16x32_bf16 v[24:27], v[136:139], v[202:205], v[24:27]
	v_mfma_f32_16x16x32_bf16 v[12:15], v[128:131], v[210:213], v[12:15]
	v_mfma_f32_16x16x32_bf16 v[8:11], v[136:139], v[210:213], v[8:11]
	v_mfma_f32_16x16x32_bf16 v[60:63], v[132:135], v[178:181], v[60:63]
	v_mfma_f32_16x16x32_bf16 v[56:59], v[140:143], v[178:181], v[56:59]
	v_mfma_f32_16x16x32_bf16 v[44:47], v[132:135], v[198:201], v[44:47]
	v_mfma_f32_16x16x32_bf16 v[40:43], v[140:143], v[198:201], v[40:43]
	v_mfma_f32_16x16x32_bf16 v[28:31], v[132:135], v[206:209], v[28:31]
	v_mfma_f32_16x16x32_bf16 v[24:27], v[140:143], v[206:209], v[24:27]
	v_mfma_f32_16x16x32_bf16 v[12:15], v[132:135], v[214:217], v[12:15]
	v_mfma_f32_16x16x32_bf16 v[8:11], v[140:143], v[214:217], v[8:11]
	v_mfma_f32_16x16x32_bf16 v[52:55], v[144:147], v[174:177], v[52:55]
	v_mfma_f32_16x16x32_bf16 v[48:51], v[166:169], v[174:177], v[48:51]
	v_mfma_f32_16x16x32_bf16 v[36:39], v[144:147], v[194:197], v[36:39]
	v_mfma_f32_16x16x32_bf16 v[32:35], v[166:169], v[194:197], v[32:35]
	v_mfma_f32_16x16x32_bf16 v[20:23], v[144:147], v[202:205], v[20:23]
	v_mfma_f32_16x16x32_bf16 v[16:19], v[166:169], v[202:205], v[16:19]
	v_mfma_f32_16x16x32_bf16 v[4:7], v[144:147], v[210:213], v[4:7]
	v_mfma_f32_16x16x32_bf16 v[0:3], v[166:169], v[210:213], v[0:3]
	v_mfma_f32_16x16x32_bf16 v[52:55], v[148:151], v[178:181], v[52:55]
	v_mfma_f32_16x16x32_bf16 v[48:51], v[170:173], v[178:181], v[48:51]
	v_mfma_f32_16x16x32_bf16 v[36:39], v[148:151], v[198:201], v[36:39]
	v_mfma_f32_16x16x32_bf16 v[32:35], v[170:173], v[198:201], v[32:35]
	v_mfma_f32_16x16x32_bf16 v[20:23], v[148:151], v[206:209], v[20:23]
	v_mfma_f32_16x16x32_bf16 v[16:19], v[170:173], v[206:209], v[16:19]
	v_mfma_f32_16x16x32_bf16 v[4:7], v[148:151], v[214:217], v[4:7]
	v_mfma_f32_16x16x32_bf16 v[0:3], v[170:173], v[214:217], v[0:3]
	s_barrier
	s_add_i32 s1, s1, 2
	s_add_u32 s4, s4, 0x100
	s_addc_u32 s5, s5, 0
	s_cmpk_gt_u32 s1, 0x53
	s_mov_b64 s[38:39], s[40:41]
	s_cbranch_scc0 .LBB0_876
	s_setprio 0
	s_and_b64 vcc, exec, s[26:27]
	s_cbranch_vccz .LBB0_879
	s_barrier
